# cvt4: table conversion in P5 software-pipelined (u rows loaded one tile ahead in stage-2 window by waves 2,3,6,7; v rows by waves 4,5 in stage-1 window), coalesced row layout
# speedup vs baseline: 1.0460x; 1.0021x over previous
; template <int WM>
; DI void gemm_tile(const u16* __restrict__ A, const u16* __restrict__ Bt, const int K, const int m0, const int n0, char* smem, f32x4 (&acc)[4][4]) {
;   constexpr int BM = 64 * WM;
;   const int tid = threadIdx.x, lane = tid & 63, w = __builtin_amdgcn_readfirstlane(tid >> 6);
;   const int wm = w % WM, wn = w / WM;
;   const int g = lane >> 4, r16 = lane & 15;
; #pragma unroll
;   for (int i = 0; i < 4; ++i)
; #pragma unroll
;     for (int j = 0; j < 4; ++j) acc[i][j] = f32x4{0.f, 0.f, 0.f, 0.f};
;   const int srow = tid >> 3, sc = tid & 7;
;   const u16* gp[6];
; #pragma unroll
;   for (int i = 0; i < 6; ++i) {
;     const int row = srow + 64 * i;
;     const int c = sc ^ ((row >> 1) & 7);
;     gp[i] = (i < WM) ? (A + (size_t)(m0 + row) * K + c * 8) : (Bt + (size_t)(n0 + row - BM) * K + c * 8);
;   }
;   lds_u32* lbase = (lds_u32*)(smem + tid * 16);
; DI void phase_peer_q(const Params& p, char* smem) {
;   const u16* h1b = (const u16*)(p.ws + WS_XB);
;   const u16* wt = (const u16*)(p.ws + WS_WQ);
;   const u16* keysb = (const u16*)(p.ws + WS_KEYS);
;   int* sel_i = (int*)(p.ws + WS_SELI);
;   float* sel_g = (float*)(p.ws + WS_SELG);
;   float* Sbuf = (float*)smem;
;   unsigned* xch = (unsigned*)(smem + 128 * 257 * 4);
;   const int tid = threadIdx.x, lane = tid & 63, w = __builtin_amdgcn_readfirstlane(tid >> 6), g = lane >> 4, r16 = lane & 15;
;   constexpr int WM = 2;
;   const int wm = w % WM, wn = w / WM;
;   for (int tile = blockIdx.x, kit = 0; tile < (T / 128) * 8; tile += gridDim.x, ++kit) {
;     int mt_, nt_; tile_coords<8>(tile, kit, T / 128, 8, mt_, nt_);
;     const int m0 = mt_ * 128, hd = nt_, n0 = hd * 256;
.LBB0_393:
	s_cmp_lt_i32 s74, 6
	s_cselect_b64 s[0:1], -1, 0
	s_and_b64 s[42:43], s[0:1], s[10:11]
	s_andn2_b64 vcc, exec, s[42:43]
	s_cbranch_vccnz .LBB0_412
	s_cmpk_gt_i32 s2, 0x7ff
	v_readfirstlane_b32 s0, v0
	s_cbranch_scc1 .LBB0_412
	s_add_u32 s44, s72, 0x4b00000
	s_load_dword s50, s[78:79], 0xa0
	s_addc_u32 s45, s73, 0
	s_add_u32 s46, s72, 0x1cc00000
	s_addc_u32 s47, s73, 0
	v_lshrrev_b32_e32 v6, 4, v0
	s_add_u32 s48, s72, 0x1dc00000
	v_xor_b32_e32 v2, v6, v0
	s_addc_u32 s49, s73, 0
	s_waitcnt lgkmcnt(0)
	s_and_b32 s1, s50, 7
	v_lshlrev_b32_e32 v2, 4, v2
	s_cmp_eq_u32 s1, 0
	v_and_b32_e32 v2, 0x70, v2
	v_mov_b32_e32 v3, 0
	s_cselect_b64 s[54:55], -1, 0
	s_cmp_lg_u32 s1, 0
	v_lshl_add_u64 v[82:83], s[72:73], 0, v[2:3]
	s_mov_b64 s[4:5], 0x4700000
	s_cselect_b64 s[56:57], -1, 0
	v_lshl_add_u64 v[84:85], v[82:83], 0, s[4:5]
	v_bfe_u32 v2, v0, 1, 3
	s_lshr_b32 s5, s0, 1
	v_and_b32_e32 v12, 0x7f, v0
	v_and_b32_e32 v14, 0x80, v0
	v_bfe_u32 v1, v0, 4, 2
	v_and_b32_e32 v106, 15, v0
	v_lshrrev_b32_e32 v4, 1, v0
	v_bitop3_b32 v5, v6, v2, 3 bitop3:0x6c
	s_and_b32 s5, s5, 0x7fffffc0
	v_mul_u32_u24_e32 v13, 0x404, v12
	v_lshlrev_b32_e32 v14, 2, v14
	v_lshlrev_b32_e32 v119, 4, v5
	v_lshlrev_b32_e32 v5, 2, v1
	v_or_b32_e32 v9, s5, v106
	v_add3_u32 v122, 0, v13, v14
	v_lshlrev_b32_e32 v13, 7, v12
	s_add_i32 s10, 0, 0x20200
	v_and_b32_e32 v4, 64, v4
	s_lshl_b32 s1, s2, 5
	v_and_or_b32 v8, s0, 64, v5
	v_add3_u32 v123, s10, v13, v4
	v_or_b32_e32 v4, 1, v5
	v_lshrrev_b32_e32 v9, 3, v9
	s_and_b32 s65, s1, 0xe0
	s_movk_i32 s1, 0x80
	s_bfe_u32 s5, s0, 0x20006
	v_or_b32_e32 v13, 2, v5
	v_lshl_add_u32 v8, v8, 9, 0
	v_bitop3_b32 v20, v9, v4, 2 bitop3:0x36
	v_bitop3_b32 v24, v9, v4, 4 bitop3:0x36
	v_bitop3_b32 v4, v9, v4, 6 bitop3:0x36
	v_lshl_or_b32 v11, s5, 5, v5
	v_cmp_gt_u32_e64 s[8:9], s1, v0
	v_or_b32_e32 v14, 3, v5
	v_lshl_add_u32 v28, v4, 4, v8
	v_bitop3_b32 v4, v9, v13, 6 bitop3:0x36
	s_lshl_b32 s1, s5, 14
	s_abs_i32 s5, s50
	v_bitop3_b32 v22, v9, v14, 2 bitop3:0x36
	v_bitop3_b32 v25, v9, v13, 4 bitop3:0x36
	v_bitop3_b32 v26, v9, v14, 4 bitop3:0x36
	v_lshl_add_u32 v13, v4, 4, v8
	v_bitop3_b32 v4, v9, v14, 6 bitop3:0x36
	v_cvt_f32_u32_e32 v14, s5
	v_bitop3_b32 v2, v1, v2, 4 bitop3:0x36
	s_lshr_b32 s6, s0, 2
	v_lshlrev_b32_e32 v121, 4, v2
	v_rcp_iflag_f32_e32 v14, v14
	v_lshlrev_b32_e32 v2, 1, v0
	s_and_b32 s6, s6, 0x3fffffc0
	v_and_b32_e32 v10, 14, v2
	v_mul_f32_e32 v14, 0x4f7ffffe, v14
	v_or_b32_e32 v2, s6, v106
	v_xor_b32_e32 v15, v9, v5
	v_bitop3_b32 v16, v9, v5, 1 bitop3:0x1e
	v_bitop3_b32 v17, v9, v5, 2 bitop3:0x1e
	v_bitop3_b32 v18, v9, v5, 3 bitop3:0x1e
	v_bitop3_b32 v19, v9, v5, 2 bitop3:0x36
	v_bitop3_b32 v21, v9, v5, 2 bitop3:0x14
	v_bitop3_b32 v23, v9, v5, 4 bitop3:0x36
	v_bitop3_b32 v5, v9, v5, 6 bitop3:0x36
	v_cvt_u32_f32_e32 v14, v14
	v_lshl_add_u32 v15, v15, 4, v8
	v_lshl_add_u32 v16, v16, 4, v8
	v_lshl_add_u32 v17, v17, 4, v8
	v_lshl_add_u32 v18, v18, 4, v8
	v_lshl_add_u32 v19, v19, 4, v8
	v_lshl_add_u32 v20, v20, 4, v8
	v_lshl_add_u32 v21, v21, 4, v8
	v_lshl_add_u32 v22, v22, 4, v8
	v_lshl_add_u32 v23, v23, 4, v8
	v_lshl_add_u32 v24, v24, 4, v8
	v_lshl_add_u32 v25, v25, 4, v8
	v_lshl_add_u32 v26, v26, 4, v8
	v_lshl_add_u32 v27, v5, 4, v8
	v_lshl_add_u32 v8, v4, 4, v8
	v_or_b32_e32 v4, 16, v2
	v_mov_b32_e32 v5, v3
	s_and_b32 s0, s0, 0xffffff00
	v_lshlrev_b64 v[86:87], 4, v[2:3]
	v_lshlrev_b64 v[88:89], 4, v[4:5]
	v_or_b32_e32 v4, 32, v2
	v_or_b32_e32 v2, 48, v2
	v_lshlrev_b32_e32 v7, 2, v106
	s_add_i32 s0, s0, 0
	v_lshlrev_b64 v[90:91], 4, v[4:5]
	v_lshlrev_b64 v[92:93], 4, v[2:3]
	v_bitop3_b32 v2, v6, v106, 3 bitop3:0x6c
	s_add_i32 s1, s1, 0
	v_bitop3_b32 v4, v1, v106, 4 bitop3:0x36
	v_bitop3_b32 v5, v1, v106, 8 bitop3:0x36
	v_bitop3_b32 v6, v1, v106, 12 bitop3:0x36
	v_bitop3_b32 v9, v1, v106, 16 bitop3:0x36
	v_bitop3_b32 v29, v1, v106, 20 bitop3:0x36
	v_bitop3_b32 v30, v1, v106, 24 bitop3:0x36
	v_bitop3_b32 v31, v1, v106, 28 bitop3:0x36
	v_mul_u32_u24_e32 v11, 0x404, v11
	v_lshl_add_u32 v2, v2, 4, s1
	v_lshl_add_u32 v4, v4, 4, s1
	v_lshl_add_u32 v5, v5, 4, s1
	v_lshl_add_u32 v6, v6, 4, s1
	v_lshl_add_u32 v9, v9, 4, s1
	v_lshl_add_u32 v29, v29, 4, s1
	v_lshl_add_u32 v30, v30, 4, s1
	v_lshl_add_u32 v31, v31, 4, s1
	v_add3_u32 v131, s0, v7, v11
	s_sub_i32 s0, 0, s5
	v_readfirstlane_b32 s1, v14
	s_mul_i32 s0, s0, s1
	s_mul_hi_u32 s0, s1, s0
	s_add_i32 s1, s1, s0
	s_lshr_b32 s0, s1, 21
	s_mul_i32 s0, s0, s5
	s_sub_i32 s0, 0x800, s0
	s_lshr_b32 s51, s2, 3
	s_ashr_i32 s64, s50, 3
	s_sub_i32 s1, s0, s5
	s_cmp_ge_u32 s0, s5
	s_cselect_b32 s0, s1, s0
	s_sub_i32 s1, s0, s5
	s_movk_i32 s4, 0x100
	s_cmp_ge_u32 s0, s5
	v_lshlrev_b32_e32 v7, 2, v0
	v_cmp_gt_u32_e64 s[6:7], s4, v0
	s_movk_i32 s4, 0x404
	s_cselect_b32 s0, s1, s0
	v_and_b32_e32 v7, 0x200, v7
	v_lshrrev_b32_e32 v107, 3, v0
	v_lshl_add_u32 v113, v0, 4, 0
	v_lshlrev_b32_e32 v3, 9, v106
	s_cmp_lg_u32 s0, 0
	v_mad_u32_u24 v7, v12, s4, v7
	s_mov_b64 s[82:83], s[76:77]
	s_mov_b64 s[84:85], s[78:79]
	s_mov_b32 s53, 0
	v_or_b32_e32 v108, 64, v107
	v_or_b32_e32 v109, 0x80, v107
	v_or_b32_e32 v110, 0xc0, v107
	v_or_b32_e32 v111, 0x100, v107
	v_or_b32_e32 v112, 0x140, v107
	v_add_u32_e32 v114, 0x10000, v113
	v_add_u32_e32 v115, 0x12000, v113
	v_add_u32_e32 v116, 0x14000, v113
	v_add_u32_e32 v117, 0x16000, v113
	v_or_b32_e32 v118, 0x80, v106
	v_or_b32_e32 v120, 4, v1
	s_movk_i32 s66, 0xff00
	s_movk_i32 s67, 0x7f
	v_lshl_add_u32 v124, v0, 7, s10
	v_or_b32_e32 v125, 8, v1
	v_or_b32_e32 v126, 12, v1
	v_or_b32_e32 v127, 16, v1
	v_or_b32_e32 v128, 20, v1
	v_or_b32_e32 v129, 24, v1
	v_or_b32_e32 v130, 28, v1
	s_cselect_b64 s[58:59], -1, 0
	v_add3_u32 v132, v7, 0, 64
	s_mov_b64 s[60:61], 0x80
	s_movk_i32 s76, 0xff
	v_add_u32_e32 v133, v15, v10
	v_add_u32_e32 v134, v16, v10
	v_add_u32_e32 v135, v17, v10
	v_add_u32_e32 v136, v18, v10
	v_add_u32_e32 v137, v19, v10
	v_add_u32_e32 v138, v20, v10
	v_add_u32_e32 v139, v21, v10
	v_add_u32_e32 v140, v22, v10
	v_add_u32_e32 v141, v23, v10
	v_add_u32_e32 v142, v24, v10
	v_add_u32_e32 v143, v25, v10
	v_add_u32_e32 v144, v26, v10
	v_add_u32_e32 v145, v27, v10
	v_add_u32_e32 v146, v28, v10
	v_add_u32_e32 v147, v13, v10
	v_add_u32_e32 v148, v8, v10
	v_add_u32_e32 v149, v2, v3
	v_add_u32_e32 v150, v4, v3
	v_add_u32_e32 v151, v5, v3
	v_add_u32_e32 v152, v6, v3
	v_add_u32_e32 v153, v9, v3
	v_add_u32_e32 v154, v29, v3
	v_add_u32_e32 v155, v30, v3
	v_add_u32_e32 v156, v31, v3
	s_mov_b32 s77, s2
	s_mov_b32 s78, 0
	v_readfirstlane_b32 s92, v0
	s_nop 3
	s_lshr_b32 s92, s92, 6
	s_bitcmp1_b32 s92, 1
	s_cbranch_scc0 .Lmy_cv_pro_done
; DI void cvt_rows_i8(const float* __restrict__ src, unsigned char* __restrict__ dst, float* __restrict__ scale_out, size_t n16, size_t gtid, size_t gsz) {
;   for (size_t i = gtid; i < n16; i += gsz) {
;     const float4 a = *(const float4*)(src + i * 16), b = *(const float4*)(src + i * 16 + 4), c = *(const float4*)(src + i * 16 + 8), d = *(const float4*)(src + i * 16 + 12);
	v_mbcnt_lo_u32_b32 v238, -1, 0
	v_mbcnt_hi_u32_b32 v238, -1, v238
	s_and_b32 s88, s92, 1
	s_lshr_b32 s89, s92, 2
	s_lshl_b32 s89, s89, 1
	s_or_b32 s88, s88, s89
	s_lshl_b32 s93, s77, 2
	s_add_u32 s93, s93, s88
	v_readlane_b32 s98, v239, 10
	v_readlane_b32 s99, v239, 11
	v_xor_b32_e32 v195, 32, v238
	v_lshlrev_b32_e32 v195, 2, v195
	v_xor_b32_e32 v196, 16, v238
	v_lshlrev_b32_e32 v196, 2, v196
	v_xor_b32_e32 v197, 8, v238
	v_lshlrev_b32_e32 v197, 2, v197
	v_xor_b32_e32 v198, 4, v238
	v_lshlrev_b32_e32 v198, 2, v198
	v_xor_b32_e32 v199, 2, v238
	v_lshlrev_b32_e32 v199, 2, v199
	v_xor_b32_e32 v218, 1, v238
	v_lshlrev_b32_e32 v218, 2, v218
	v_lshlrev_b32_e32 v219, 4, v238
	v_lshlrev_b32_e32 v220, 2, v238
	v_mov_b32_e32 v221, 0
	v_cmp_eq_u32_e64 s[90:91], 0, v238
	s_mov_b32 s97, 0x42fe0000
	s_mov_b32 s96, 0xda24260
	s_mov_b32 s89, s93
	s_lshl_b32 s88, s89, 12
	s_add_u32 s86, s98, s88
	s_addc_u32 s87, s99, 0
	global_load_dwordx4 v[202:205], v219, s[86:87] nt
	global_load_dwordx4 v[206:209], v219, s[86:87] offset:1024 nt
	global_load_dwordx4 v[210:213], v219, s[86:87] offset:2048 nt
	global_load_dwordx4 v[214:217], v219, s[86:87] offset:3072 nt
	s_add_u32 s89, s93, 8192
	s_lshl_b32 s88, s89, 12
	s_add_u32 s86, s98, s88
	s_addc_u32 s87, s99, 0
	global_load_dwordx4 v[240:243], v219, s[86:87] nt
	global_load_dwordx4 v[244:247], v219, s[86:87] offset:1024 nt
	global_load_dwordx4 v[248:251], v219, s[86:87] offset:2048 nt
	global_load_dwordx4 v[252:255], v219, s[86:87] offset:3072 nt
.Lmy_cv_pro_done:
	s_branch .LBB0_397

; #define MFMA16(a, b, c) __builtin_amdgcn_mfma_f32_16x16x32_bf16((a), (b), (c), 0, 0, 0)
; #define STAGE(KOFF, BUF) do { \
;     _Pragma("unroll") for (int i = 0; i < 6; ++i) \
;       __builtin_amdgcn_global_load_lds((const unsigned*)(gp[i] + (KOFF)), (lds_u32*)((__attribute__((address_space(3))) char*)lbase + (BUF) * STAGE_BYTES + i * 8192), 16, 0, 0); } while (0)
; template <int WM>
; DI void gemm_tile(const u16* __restrict__ A, const u16* __restrict__ Bt, const int K, const int m0, const int n0, char* smem, f32x4 (&acc)[4][4]) {
;     ...
;   for (int kt = 0; kt < KT; ++kt) {
;     asm volatile("s_waitcnt vmcnt(6)" ::: "memory");
;     __builtin_amdgcn_s_barrier();
;     const int kn = (kt + 2 < KT ? kt + 2 : KT - 1) * 64;
;     const int bn = (kt + 2) % 3, bc = kt % 3;
;     STAGE(kn, bn);
;     const char* cur = smem + bc * STAGE_BYTES;
;     bf16x8 af[2][4], bfr[2][4];
; #pragma unroll
;     for (int kk = 0; kk < 2; ++kk) {
;       const int c = 4 * kk + g;
; #pragma unroll
;       for (int mi = 0; mi < 4; ++mi) { const int row = 64 * wm + 16 * mi + r16; af[kk][mi] = *(const bf16x8*)(cur + row * 128 + ((c ^ ((row >> 1) & 7)) << 4)); }
; #pragma unroll
;       for (int ni = 0; ni < 4; ++ni) { const int row = BM + 64 * wn + 16 * ni + r16; bfr[kk][ni] = *(const bf16x8*)(cur + row * 128 + ((c ^ ((row >> 1) & 7)) << 4)); }
;     }
; #pragma unroll
;     for (int kk = 0; kk < 2; ++kk)
; #pragma unroll
;       for (int mi = 0; mi < 4; ++mi)
; #pragma unroll
;         for (int ni = 0; ni < 4; ++ni) acc[mi][ni] = MFMA16(af[kk][mi], bfr[kk][ni], acc[mi][ni]);
;   }
.LBB0_402:
	s_cmp_lt_u32 s0, 14
	s_mul_i32 s4, s0, 0xab
	s_cselect_b32 s52, s1, 0x3c0
	s_add_i32 s5, s4, 0x156
	s_bfe_u32 s4, s4, 0x70009
	s_bfe_u32 s10, s5, 0x70009
	s_mul_i32 s11, s4, 3
	s_lshl_b64 s[4:5], s[52:53], 1
	s_mul_i32 s10, s10, 3
	v_lshl_add_u64 v[160:161], v[94:95], 0, s[4:5]
	v_lshl_add_u64 v[162:163], v[96:97], 0, s[4:5]
	v_lshl_add_u64 v[164:165], v[98:99], 0, s[4:5]
	v_lshl_add_u64 v[166:167], v[100:101], 0, s[4:5]
	v_lshl_add_u64 v[168:169], v[102:103], 0, s[4:5]
	v_lshl_add_u64 v[170:171], v[104:105], 0, s[4:5]
	s_sub_i32 s4, s0, s10
	s_add_i32 s4, s4, 2
	s_and_b32 s4, s4, 0xff
	s_mul_i32 s4, s4, 0xc000
	v_add_u32_e32 v172, s4, v113
	v_add_u32_e32 v173, 0x2000, v172
	v_readfirstlane_b32 s4, v172
	s_sub_i32 s11, s0, s11
	v_add_u32_e32 v174, 0x4000, v172
	v_readfirstlane_b32 s10, v173
	s_mov_b32 m0, s4
	s_waitcnt vmcnt(6)
	s_barrier
	s_and_b32 s5, s11, 0xff
	v_add_u32_e32 v175, 0x6000, v172
	v_readfirstlane_b32 s11, v174
	global_load_lds_dwordx4 v[160:161], off
	s_mov_b32 m0, s10
	v_add_u32_e32 v176, 0x8000, v172
	v_readfirstlane_b32 s12, v175
	global_load_lds_dwordx4 v[162:163], off
	s_mov_b32 m0, s11
	v_add_u32_e32 v172, 0xa000, v172
	v_readfirstlane_b32 s13, v176
	global_load_lds_dwordx4 v[164:165], off
	s_mov_b32 m0, s12
	v_readfirstlane_b32 s14, v172
	global_load_lds_dwordx4 v[166:167], off
	s_mov_b32 m0, s13
	s_mul_i32 s5, s5, 0xc000
	global_load_lds_dwordx4 v[168:169], off
	s_mov_b32 m0, s14
	s_add_i32 s5, s5, 0
	global_load_lds_dwordx4 v[170:171], off
	v_add_u32_e32 v159, s5, v119
	v_add_u32_e32 v184, v159, v158
	v_add_u32_e32 v159, v159, v157
	ds_read_b128 v[160:163], v184
	ds_read_b128 v[164:167], v159
	ds_read_b128 v[168:171], v184 offset:2048
	ds_read_b128 v[172:175], v159 offset:2048
	ds_read_b128 v[176:179], v159 offset:4096
	ds_read_b128 v[180:183], v159 offset:6144
	s_waitcnt lgkmcnt(0)
	v_mfma_f32_16x16x32_bf16 v[78:81], v[160:163], v[164:167], v[78:81]
	v_add_u32_e32 v159, s5, v121
	s_add_i32 s1, s1, 64
	s_add_i32 s0, s0, 1
	v_mfma_f32_16x16x32_bf16 v[74:77], v[160:163], v[172:175], v[74:77]
	s_cmpk_lg_i32 s1, 0x480
	v_mfma_f32_16x16x32_bf16 v[70:73], v[160:163], v[176:179], v[70:73]
	v_mfma_f32_16x16x32_bf16 v[66:69], v[160:163], v[180:183], v[66:69]
	v_mfma_f32_16x16x32_bf16 v[62:65], v[168:171], v[164:167], v[62:65]
	v_mfma_f32_16x16x32_bf16 v[58:61], v[168:171], v[172:175], v[58:61]
	v_mfma_f32_16x16x32_bf16 v[54:57], v[168:171], v[176:179], v[54:57]
	v_mfma_f32_16x16x32_bf16 v[50:53], v[168:171], v[180:183], v[50:53]
	ds_read_b128 v[160:163], v184 offset:4096
	ds_read_b128 v[168:171], v184 offset:6144
	v_add_u32_e32 v184, v159, v158
	v_add_u32_e32 v159, v159, v157
	s_waitcnt lgkmcnt(0)
	v_mfma_f32_16x16x32_bf16 v[46:49], v[160:163], v[164:167], v[46:49]
	v_mfma_f32_16x16x32_bf16 v[42:45], v[160:163], v[172:175], v[42:45]
	v_mfma_f32_16x16x32_bf16 v[38:41], v[160:163], v[176:179], v[38:41]
	v_mfma_f32_16x16x32_bf16 v[30:33], v[160:163], v[180:183], v[30:33]
	ds_read_b128 v[160:163], v184
	v_mfma_f32_16x16x32_bf16 v[26:29], v[168:171], v[164:167], v[26:29]
	v_mfma_f32_16x16x32_bf16 v[22:25], v[168:171], v[172:175], v[22:25]
	v_mfma_f32_16x16x32_bf16 v[18:21], v[168:171], v[176:179], v[18:21]
	v_mfma_f32_16x16x32_bf16 v[34:37], v[168:171], v[180:183], v[34:37]
	ds_read_b128 v[164:167], v159
	ds_read_b128 v[168:171], v184 offset:2048
	ds_read_b128 v[172:175], v159 offset:2048
	ds_read_b128 v[176:179], v159 offset:4096
	ds_read_b128 v[180:183], v159 offset:6144
	s_waitcnt lgkmcnt(0)
	v_mfma_f32_16x16x32_bf16 v[78:81], v[160:163], v[164:167], v[78:81]
	v_mfma_f32_16x16x32_bf16 v[74:77], v[160:163], v[172:175], v[74:77]
	v_mfma_f32_16x16x32_bf16 v[70:73], v[160:163], v[176:179], v[70:73]
	v_mfma_f32_16x16x32_bf16 v[66:69], v[160:163], v[180:183], v[66:69]
	v_mfma_f32_16x16x32_bf16 v[62:65], v[168:171], v[164:167], v[62:65]
	v_mfma_f32_16x16x32_bf16 v[58:61], v[168:171], v[172:175], v[58:61]
	v_mfma_f32_16x16x32_bf16 v[54:57], v[168:171], v[176:179], v[54:57]
	v_mfma_f32_16x16x32_bf16 v[50:53], v[168:171], v[180:183], v[50:53]
	ds_read_b128 v[160:163], v184 offset:4096
	ds_read_b128 v[168:171], v184 offset:6144
	s_waitcnt lgkmcnt(0)
	v_mfma_f32_16x16x32_bf16 v[46:49], v[160:163], v[164:167], v[46:49]
	v_mfma_f32_16x16x32_bf16 v[42:45], v[160:163], v[172:175], v[42:45]
	v_mfma_f32_16x16x32_bf16 v[38:41], v[160:163], v[176:179], v[38:41]
	v_mfma_f32_16x16x32_bf16 v[30:33], v[160:163], v[180:183], v[30:33]
	v_mfma_f32_16x16x32_bf16 v[26:29], v[168:171], v[164:167], v[26:29]
	v_mfma_f32_16x16x32_bf16 v[22:25], v[168:171], v[172:175], v[22:25]
	v_mfma_f32_16x16x32_bf16 v[18:21], v[168:171], v[176:179], v[18:21]
	v_mfma_f32_16x16x32_bf16 v[34:37], v[168:171], v[180:183], v[34:37]
	s_cbranch_scc1 .LBB0_402
	v_cvt_pk_bf16_f32 v78, v78, s0
	s_waitcnt vmcnt(0)
	s_waitcnt vmcnt(0)
	s_barrier
; DI u16 f2bf(float x) { return (u16)(pack2(x, x) & 0xffffu); }
; DI void phase_peer_q(const Params& p, char* smem) {
;     ...
; #pragma unroll
;       for (int mi = 0; mi < 4; ++mi)
; #pragma unroll
;         for (int ni = 0; ni < 4; ++ni)
; #pragma unroll
;           for (int j = 0; j < 4; ++j) {
;             const int row = 64 * wm + 16 * mi + 4 * g + j, col = 64 * wn + 16 * ni + r16;
;             *(u16*)(smem + row * 512 + (((col >> 3) ^ (row & 15)) << 4) + (col & 7) * 2) = f2bf(acc[mi][ni][j]);
;           }
;     }
;     __syncthreads();
;     ...
; #pragma unroll
;         for (int kk = 0; kk < 4; ++kk)
; #pragma unroll
;           for (int ni = 0; ni < 4; ++ni) {
;             const int n = 64 * swn + 16 * ni + r16;
;             bfr[kk][ni] = *(const bf16x8*)(keysb + ((size_t)(((hd * 2 + pp) * 4 + kk) * 4 + g) * 128 + n) * 8);
;           }
	ds_write_b16 v133, v78
	v_cvt_pk_bf16_f32 v78, v79, s0
	ds_write_b16 v134, v78 offset:512
	v_cvt_pk_bf16_f32 v78, v80, s0
	ds_write_b16 v135, v78 offset:1024
	v_cvt_pk_bf16_f32 v78, v81, s0
	v_cvt_pk_bf16_f32 v74, v74, s0
	ds_write_b16 v136, v78 offset:1536
	ds_write_b16 v137, v74
	v_cvt_pk_bf16_f32 v74, v75, s0
	ds_write_b16 v138, v74 offset:512
	v_cvt_pk_bf16_f32 v74, v76, s0
	ds_write_b16 v139, v74 offset:1024
	v_cvt_pk_bf16_f32 v74, v77, s0
	v_cvt_pk_bf16_f32 v70, v70, s0
	ds_write_b16 v140, v74 offset:1536
	ds_write_b16 v141, v70
	v_cvt_pk_bf16_f32 v70, v71, s0
	ds_write_b16 v142, v70 offset:512
	v_cvt_pk_bf16_f32 v70, v72, s0
	ds_write_b16 v143, v70 offset:1024
	v_cvt_pk_bf16_f32 v70, v73, s0
	v_cvt_pk_bf16_f32 v66, v66, s0
	ds_write_b16 v144, v70 offset:1536
	ds_write_b16 v145, v66
	v_cvt_pk_bf16_f32 v66, v67, s0
	ds_write_b16 v146, v66 offset:512
	v_cvt_pk_bf16_f32 v66, v68, s0
	ds_write_b16 v147, v66 offset:1024
	v_cvt_pk_bf16_f32 v66, v69, s0
	v_cvt_pk_bf16_f32 v62, v62, s0
	ds_write_b16 v148, v66 offset:1536
	ds_write_b16 v133, v62 offset:8192
	v_cvt_pk_bf16_f32 v62, v63, s0
	ds_write_b16 v134, v62 offset:8704
	v_cvt_pk_bf16_f32 v62, v64, s0
	ds_write_b16 v135, v62 offset:9216
	v_cvt_pk_bf16_f32 v62, v65, s0
	v_cvt_pk_bf16_f32 v58, v58, s0
	ds_write_b16 v136, v62 offset:9728
	ds_write_b16 v137, v58 offset:8192
	v_cvt_pk_bf16_f32 v58, v59, s0
	ds_write_b16 v138, v58 offset:8704
	v_cvt_pk_bf16_f32 v58, v60, s0
	ds_write_b16 v139, v58 offset:9216
	v_cvt_pk_bf16_f32 v58, v61, s0
	v_cvt_pk_bf16_f32 v54, v54, s0
	ds_write_b16 v140, v58 offset:9728
	ds_write_b16 v141, v54 offset:8192
	v_cvt_pk_bf16_f32 v54, v55, s0
	ds_write_b16 v142, v54 offset:8704
	v_cvt_pk_bf16_f32 v54, v56, s0
	ds_write_b16 v143, v54 offset:9216
	v_cvt_pk_bf16_f32 v54, v57, s0
	v_cvt_pk_bf16_f32 v50, v50, s0
	ds_write_b16 v144, v54 offset:9728
	ds_write_b16 v145, v50 offset:8192
	v_cvt_pk_bf16_f32 v50, v51, s0
	ds_write_b16 v146, v50 offset:8704
	v_cvt_pk_bf16_f32 v50, v52, s0
	ds_write_b16 v147, v50 offset:9216
	v_cvt_pk_bf16_f32 v50, v53, s0
	v_cvt_pk_bf16_f32 v46, v46, s0
	ds_write_b16 v148, v50 offset:9728
	ds_write_b16 v133, v46 offset:16384
	v_cvt_pk_bf16_f32 v46, v47, s0
	ds_write_b16 v134, v46 offset:16896
	v_cvt_pk_bf16_f32 v46, v48, s0
	ds_write_b16 v135, v46 offset:17408
	v_cvt_pk_bf16_f32 v46, v49, s0
	v_cvt_pk_bf16_f32 v42, v42, s0
	ds_write_b16 v136, v46 offset:17920
	ds_write_b16 v137, v42 offset:16384
	v_cvt_pk_bf16_f32 v42, v43, s0
	ds_write_b16 v138, v42 offset:16896
	v_cvt_pk_bf16_f32 v42, v44, s0
	ds_write_b16 v139, v42 offset:17408
	v_cvt_pk_bf16_f32 v42, v45, s0
	v_cvt_pk_bf16_f32 v38, v38, s0
	ds_write_b16 v140, v42 offset:17920
	ds_write_b16 v141, v38 offset:16384
	v_cvt_pk_bf16_f32 v38, v39, s0
	ds_write_b16 v142, v38 offset:16896
	v_cvt_pk_bf16_f32 v38, v40, s0
	ds_write_b16 v143, v38 offset:17408
	v_cvt_pk_bf16_f32 v38, v41, s0
	v_cvt_pk_bf16_f32 v30, v30, s0
	ds_write_b16 v144, v38 offset:17920
	ds_write_b16 v145, v30 offset:16384
	v_cvt_pk_bf16_f32 v30, v31, s0
	ds_write_b16 v146, v30 offset:16896
	v_cvt_pk_bf16_f32 v30, v32, s0
	ds_write_b16 v147, v30 offset:17408
	v_cvt_pk_bf16_f32 v30, v33, s0
	v_cvt_pk_bf16_f32 v26, v26, s0
	ds_write_b16 v148, v30 offset:17920
	ds_write_b16 v133, v26 offset:24576
	v_cvt_pk_bf16_f32 v26, v27, s0
	ds_write_b16 v134, v26 offset:25088
	v_cvt_pk_bf16_f32 v26, v28, s0
	ds_write_b16 v135, v26 offset:25600
	v_cvt_pk_bf16_f32 v26, v29, s0
	v_cvt_pk_bf16_f32 v22, v22, s0
	ds_write_b16 v136, v26 offset:26112
	ds_write_b16 v137, v22 offset:24576
	v_cvt_pk_bf16_f32 v22, v23, s0
	ds_write_b16 v138, v22 offset:25088
	v_cvt_pk_bf16_f32 v22, v24, s0
	ds_write_b16 v139, v22 offset:25600
	v_cvt_pk_bf16_f32 v22, v25, s0
	v_cvt_pk_bf16_f32 v18, v18, s0
	ds_write_b16 v140, v22 offset:26112
	ds_write_b16 v141, v18 offset:24576
	v_cvt_pk_bf16_f32 v18, v19, s0
	ds_write_b16 v142, v18 offset:25088
	v_cvt_pk_bf16_f32 v18, v20, s0
	ds_write_b16 v143, v18 offset:25600
	v_cvt_pk_bf16_f32 v18, v21, s0
	ds_write_b16 v144, v18 offset:26112
	v_cvt_pk_bf16_f32 v18, v34, s0
	ds_write_b16 v145, v18 offset:24576
	v_cvt_pk_bf16_f32 v18, v35, s0
	ds_write_b16 v146, v18 offset:25088
	v_cvt_pk_bf16_f32 v18, v36, s0
	ds_write_b16 v147, v18 offset:25600
	v_cvt_pk_bf16_f32 v18, v37, s0
	s_lshl_b32 s0, s79, 5
	ds_write_b16 v148, v18 offset:26112
	v_or_b32_e32 v18, s0, v1
	v_ashrrev_i32_e32 v19, 31, v18
	v_lshlrev_b64 v[18:19], 11, v[18:19]
	v_lshl_add_u64 v[42:43], s[44:45], 0, v[18:19]
	v_lshl_add_u64 v[18:19], v[42:43], 0, v[86:87]
	v_lshl_add_u64 v[22:23], v[42:43], 0, v[88:89]
	v_lshl_add_u64 v[38:39], v[42:43], 0, v[90:91]
	v_lshl_add_u64 v[46:47], v[42:43], 0, v[92:93]
	s_waitcnt lgkmcnt(0)
	s_barrier
; #define MFMA16(a, b, c) __builtin_amdgcn_mfma_f32_16x16x32_bf16((a), (b), (c), 0, 0, 0)
; DI void phase_peer_q(const Params& p, char* smem) {
;     ...
;         bf16x8 bfr[4][4];
; #pragma unroll
;         for (int kk = 0; kk < 4; ++kk)
; #pragma unroll
;           for (int ni = 0; ni < 4; ++ni) {
;             const int n = 64 * swn + 16 * ni + r16;
;             bfr[kk][ni] = *(const bf16x8*)(keysb + ((size_t)(((hd * 2 + pp) * 4 + kk) * 4 + g) * 128 + n) * 8);
;           }
; #pragma unroll
;         for (int kk = 0; kk < 4; ++kk) {
;           bf16x8 af[2];
; #pragma unroll
;           for (int mi = 0; mi < 2; ++mi) {
;             const int row = 32 * swm + 16 * mi + r16, c = 16 * pp + 4 * kk + g;
;             af[mi] = *(const bf16x8*)(smem + row * 512 + ((c ^ (row & 15)) << 4));
;           }
; #pragma unroll
;           for (int mi = 0; mi < 2; ++mi)
; #pragma unroll
;             for (int ni = 0; ni < 4; ++ni) sc[pp][mi][ni] = MFMA16(af[mi], bfr[kk][ni], sc[pp][mi][ni]);
;         }
	global_load_dwordx4 v[18:21], v[18:19], off
	v_or_b32_e32 v54, s0, v120
	global_load_dwordx4 v[22:25], v[22:23], off
	v_ashrrev_i32_e32 v55, 31, v54
	global_load_dwordx4 v[38:41], v[38:39], off
	v_lshlrev_b64 v[54:55], 11, v[54:55]
	global_load_dwordx4 v[46:49], v[46:47], off
	v_lshl_add_u64 v[70:71], s[44:45], 0, v[54:55]
	v_lshl_add_u64 v[54:55], v[70:71], 0, v[86:87]
	v_lshl_add_u64 v[58:59], v[70:71], 0, v[88:89]
	v_lshl_add_u64 v[66:67], v[70:71], 0, v[90:91]
	v_lshl_add_u64 v[70:71], v[70:71], 0, v[92:93]
	global_load_dwordx4 v[54:57], v[54:55], off
	ds_read_b128 v[26:29], v149
	ds_read_b128 v[30:33], v149 offset:8192
	global_load_dwordx4 v[58:61], v[58:59], off
	s_waitcnt vmcnt(5) lgkmcnt(1)
	v_mfma_f32_16x16x32_bf16 v[34:37], v[26:29], v[18:21], 0
	global_load_dwordx4 v[66:69], v[66:67], off
	ds_read_b128 v[62:65], v150 offset:8192
	global_load_dwordx4 v[70:73], v[70:71], off
	s_waitcnt vmcnt(6)
	v_mfma_f32_16x16x32_bf16 v[42:45], v[26:29], v[22:25], 0
	v_or_b32_e32 v98, s0, v128
	v_ashrrev_i32_e32 v99, 31, v98
	v_lshlrev_b64 v[98:99], 11, v[98:99]
	s_waitcnt vmcnt(5)
	v_mfma_f32_16x16x32_bf16 v[50:53], v[26:29], v[38:41], 0
	v_lshl_add_u64 v[166:167], s[44:45], 0, v[98:99]
	v_lshl_add_u64 v[98:99], v[166:167], 0, v[86:87]
	v_lshl_add_u64 v[102:103], v[166:167], 0, v[88:89]
	s_waitcnt vmcnt(4)
	v_mfma_f32_16x16x32_bf16 v[26:29], v[26:29], v[46:49], 0
	v_lshl_add_u64 v[162:163], v[166:167], 0, v[90:91]
	v_lshl_add_u64 v[166:167], v[166:167], 0, v[92:93]
	global_load_dwordx4 v[98:101], v[98:99], off
	s_waitcnt lgkmcnt(1)
	v_mfma_f32_16x16x32_bf16 v[18:21], v[30:33], v[18:21], 0
	global_load_dwordx4 v[102:105], v[102:103], off
	ds_read_b128 v[158:161], v154 offset:8192
	global_load_dwordx4 v[162:165], v[162:163], off
	v_mfma_f32_16x16x32_bf16 v[22:25], v[30:33], v[22:25], 0
	global_load_dwordx4 v[166:169], v[166:167], off
	v_mfma_f32_16x16x32_bf16 v[38:41], v[30:33], v[38:41], 0
	v_mfma_f32_16x16x32_bf16 v[30:33], v[30:33], v[46:49], 0
	ds_read_b128 v[46:49], v150
	s_waitcnt vmcnt(7) lgkmcnt(0)
	v_mfma_f32_16x16x32_bf16 v[34:37], v[46:49], v[54:57], v[34:37]
	s_waitcnt vmcnt(6)
	v_mfma_f32_16x16x32_bf16 v[42:45], v[46:49], v[58:61], v[42:45]
	s_waitcnt vmcnt(5)
	v_mfma_f32_16x16x32_bf16 v[50:53], v[46:49], v[66:69], v[50:53]
	s_waitcnt vmcnt(4)
	v_mfma_f32_16x16x32_bf16 v[26:29], v[46:49], v[70:73], v[26:29]
	v_or_b32_e32 v46, s0, v125
	v_ashrrev_i32_e32 v47, 31, v46
	v_lshlrev_b64 v[46:47], 11, v[46:47]
	v_lshl_add_u64 v[74:75], s[44:45], 0, v[46:47]
	v_mfma_f32_16x16x32_bf16 v[18:21], v[62:65], v[54:57], v[18:21]
	v_lshl_add_u64 v[46:47], v[74:75], 0, v[86:87]
	v_lshl_add_u64 v[54:55], v[74:75], 0, v[88:89]
	global_load_dwordx4 v[46:49], v[46:47], off
	v_mfma_f32_16x16x32_bf16 v[38:41], v[62:65], v[66:69], v[38:41]
	v_lshl_add_u64 v[66:67], v[74:75], 0, v[90:91]
	global_load_dwordx4 v[54:57], v[54:55], off
	v_mfma_f32_16x16x32_bf16 v[30:33], v[62:65], v[70:73], v[30:33]
	v_lshl_add_u64 v[70:71], v[74:75], 0, v[92:93]
	global_load_dwordx4 v[66:69], v[66:67], off
	s_nop 0
	global_load_dwordx4 v[70:73], v[70:71], off
	v_mfma_f32_16x16x32_bf16 v[22:25], v[62:65], v[58:61], v[22:25]
	ds_read_b128 v[58:61], v151
	ds_read_b128 v[62:65], v151 offset:8192
	s_waitcnt vmcnt(3) lgkmcnt(1)
	v_mfma_f32_16x16x32_bf16 v[34:37], v[58:61], v[46:49], v[34:37]
	s_waitcnt vmcnt(2)
	v_mfma_f32_16x16x32_bf16 v[42:45], v[58:61], v[54:57], v[42:45]
	s_waitcnt vmcnt(1)
	v_mfma_f32_16x16x32_bf16 v[50:53], v[58:61], v[66:69], v[50:53]
	s_waitcnt vmcnt(0)
	v_mfma_f32_16x16x32_bf16 v[26:29], v[58:61], v[70:73], v[26:29]
	v_or_b32_e32 v58, s0, v126
	v_ashrrev_i32_e32 v59, 31, v58
	s_waitcnt lgkmcnt(0)
	v_mfma_f32_16x16x32_bf16 v[18:21], v[62:65], v[46:49], v[18:21]
	v_lshlrev_b64 v[46:47], 11, v[58:59]
	v_lshl_add_u64 v[74:75], s[44:45], 0, v[46:47]
	v_lshl_add_u64 v[46:47], v[74:75], 0, v[86:87]
	global_load_dwordx4 v[46:49], v[46:47], off
	v_mfma_f32_16x16x32_bf16 v[22:25], v[62:65], v[54:57], v[22:25]
	v_lshl_add_u64 v[54:55], v[74:75], 0, v[88:89]
	global_load_dwordx4 v[54:57], v[54:55], off
	ds_read_b128 v[58:61], v152
	v_mfma_f32_16x16x32_bf16 v[38:41], v[62:65], v[66:69], v[38:41]
	v_lshl_add_u64 v[66:67], v[74:75], 0, v[90:91]
	global_load_dwordx4 v[66:69], v[66:67], off
	v_mfma_f32_16x16x32_bf16 v[30:33], v[62:65], v[70:73], v[30:33]
	v_lshl_add_u64 v[70:71], v[74:75], 0, v[92:93]
	global_load_dwordx4 v[70:73], v[70:71], off
	ds_read_b128 v[62:65], v152 offset:8192
	s_waitcnt vmcnt(3) lgkmcnt(1)
	v_mfma_f32_16x16x32_bf16 v[34:37], v[58:61], v[46:49], v[34:37]
	s_waitcnt lgkmcnt(0)
	v_mfma_f32_16x16x32_bf16 v[18:21], v[62:65], v[46:49], v[18:21]
	v_or_b32_e32 v46, s0, v127
	v_ashrrev_i32_e32 v47, 31, v46
	v_lshlrev_b64 v[46:47], 11, v[46:47]
	v_lshl_add_u64 v[74:75], s[44:45], 0, v[46:47]
	s_waitcnt vmcnt(2)
	v_mfma_f32_16x16x32_bf16 v[42:45], v[58:61], v[54:57], v[42:45]
	v_lshl_add_u64 v[46:47], v[74:75], 0, v[86:87]
	v_lshl_add_u64 v[78:79], v[74:75], 0, v[92:93]
	global_load_dwordx4 v[46:49], v[46:47], off
	s_waitcnt vmcnt(1)
	v_mfma_f32_16x16x32_bf16 v[26:29], v[58:61], v[70:73], v[26:29]
	global_load_dwordx4 v[78:81], v[78:79], off
	v_mfma_f32_16x16x32_bf16 v[22:25], v[62:65], v[54:57], v[22:25]
	v_lshl_add_u64 v[54:55], v[74:75], 0, v[88:89]
	global_load_dwordx4 v[54:57], v[54:55], off
	v_mfma_f32_16x16x32_bf16 v[30:33], v[62:65], v[70:73], v[30:33]
	v_lshl_add_u64 v[70:71], v[74:75], 0, v[90:91]
	global_load_dwordx4 v[70:73], v[70:71], off
	v_mfma_f32_16x16x32_bf16 v[50:53], v[58:61], v[66:69], v[50:53]
	ds_read_b128 v[58:61], v153
	v_mfma_f32_16x16x32_bf16 v[38:41], v[62:65], v[66:69], v[38:41]
	ds_read_b128 v[62:65], v153 offset:8192
	s_waitcnt vmcnt(3) lgkmcnt(1)
; #define MFMA16(a, b, c) __builtin_amdgcn_mfma_f32_16x16x32_bf16((a), (b), (c), 0, 0, 0)
; DI void phase_peer_q(const Params& p, char* smem) {
;     ...
; #pragma unroll
;           for (int mi = 0; mi < 2; ++mi)
; #pragma unroll
;             for (int ni = 0; ni < 4; ++ni) sc[pp][mi][ni] = MFMA16(af[mi], bfr[kk][ni], sc[pp][mi][ni]);
;         }
;       }
;       __syncthreads();
; #pragma unroll
;       for (int pp = 0; pp < 2; ++pp)
; #pragma unroll
;         for (int mi = 0; mi < 2; ++mi)
; #pragma unroll
;           for (int ni = 0; ni < 4; ++ni)
; #pragma unroll
;             for (int j = 0; j < 4; ++j) {
;               const int row = 32 * swm + 16 * mi + 4 * g + j, n = 64 * swn + 16 * ni + r16;
;               Sbuf[row * 257 + pp * 128 + n] = sc[pp][mi][ni][j];
	v_mfma_f32_16x16x32_bf16 v[66:69], v[58:61], v[46:49], 0
	s_waitcnt vmcnt(1)
	v_mfma_f32_16x16x32_bf16 v[74:77], v[58:61], v[54:57], 0
	s_waitcnt vmcnt(0)
	v_mfma_f32_16x16x32_bf16 v[94:97], v[58:61], v[70:73], 0
	v_mfma_f32_16x16x32_bf16 v[58:61], v[58:61], v[78:81], 0
	s_waitcnt lgkmcnt(0)
	v_mfma_f32_16x16x32_bf16 v[46:49], v[62:65], v[46:49], 0
	v_mfma_f32_16x16x32_bf16 v[54:57], v[62:65], v[54:57], 0
	v_mfma_f32_16x16x32_bf16 v[70:73], v[62:65], v[70:73], 0
	v_mfma_f32_16x16x32_bf16 v[62:65], v[62:65], v[78:81], 0
	ds_read_b128 v[78:81], v154
	s_waitcnt lgkmcnt(0)
	v_mfma_f32_16x16x32_bf16 v[66:69], v[78:81], v[98:101], v[66:69]
	v_mfma_f32_16x16x32_bf16 v[74:77], v[78:81], v[102:105], v[74:77]
	v_mfma_f32_16x16x32_bf16 v[94:97], v[78:81], v[162:165], v[94:97]
	v_mfma_f32_16x16x32_bf16 v[58:61], v[78:81], v[166:169], v[58:61]
	v_or_b32_e32 v78, s0, v129
	v_ashrrev_i32_e32 v79, 31, v78
	v_lshlrev_b64 v[78:79], 11, v[78:79]
	v_lshl_add_u64 v[170:171], s[44:45], 0, v[78:79]
	v_mfma_f32_16x16x32_bf16 v[46:49], v[158:161], v[98:101], v[46:49]
	v_lshl_add_u64 v[78:79], v[170:171], 0, v[86:87]
	v_lshl_add_u64 v[98:99], v[170:171], 0, v[88:89]
	global_load_dwordx4 v[78:81], v[78:79], off
	v_mfma_f32_16x16x32_bf16 v[70:73], v[158:161], v[162:165], v[70:73]
	v_lshl_add_u64 v[162:163], v[170:171], 0, v[90:91]
	global_load_dwordx4 v[98:101], v[98:99], off
	v_mfma_f32_16x16x32_bf16 v[62:65], v[158:161], v[166:169], v[62:65]
	v_lshl_add_u64 v[166:167], v[170:171], 0, v[92:93]
	global_load_dwordx4 v[162:165], v[162:163], off
	s_nop 0
	global_load_dwordx4 v[166:169], v[166:167], off
	v_mfma_f32_16x16x32_bf16 v[54:57], v[158:161], v[102:105], v[54:57]
	ds_read_b128 v[102:105], v155
	ds_read_b128 v[158:161], v155 offset:8192
	s_waitcnt vmcnt(3) lgkmcnt(1)
	v_mfma_f32_16x16x32_bf16 v[66:69], v[102:105], v[78:81], v[66:69]
	s_waitcnt vmcnt(2)
	v_mfma_f32_16x16x32_bf16 v[74:77], v[102:105], v[98:101], v[74:77]
	s_waitcnt vmcnt(1)
	v_mfma_f32_16x16x32_bf16 v[94:97], v[102:105], v[162:165], v[94:97]
	s_waitcnt vmcnt(0)
	v_mfma_f32_16x16x32_bf16 v[58:61], v[102:105], v[166:169], v[58:61]
	v_or_b32_e32 v102, s0, v130
	v_ashrrev_i32_e32 v103, 31, v102
	s_waitcnt lgkmcnt(0)
	v_mfma_f32_16x16x32_bf16 v[46:49], v[158:161], v[78:81], v[46:49]
	v_lshlrev_b64 v[78:79], 11, v[102:103]
	v_lshl_add_u64 v[170:171], s[44:45], 0, v[78:79]
	v_lshl_add_u64 v[78:79], v[170:171], 0, v[86:87]
	v_mfma_f32_16x16x32_bf16 v[54:57], v[158:161], v[98:101], v[54:57]
	v_lshl_add_u64 v[98:99], v[170:171], 0, v[88:89]
	global_load_dwordx4 v[78:81], v[78:79], off
	ds_read_b128 v[102:105], v156
	v_mfma_f32_16x16x32_bf16 v[70:73], v[158:161], v[162:165], v[70:73]
	v_lshl_add_u64 v[162:163], v[170:171], 0, v[90:91]
	global_load_dwordx4 v[98:101], v[98:99], off
	v_mfma_f32_16x16x32_bf16 v[62:65], v[158:161], v[166:169], v[62:65]
	v_lshl_add_u64 v[166:167], v[170:171], 0, v[92:93]
	global_load_dwordx4 v[162:165], v[162:163], off
	ds_read_b128 v[158:161], v156 offset:8192
	global_load_dwordx4 v[166:169], v[166:167], off
	s_waitcnt lgkmcnt(0)
	s_barrier
	ds_write2_b32 v131, v34, v42 offset1:16
	v_add_u32_e32 v34, 0x400, v131
	ds_write2_b32 v34, v35, v43 offset0:1 offset1:17
	v_add_u32_e32 v35, 0x800, v131
	ds_write2_b32 v35, v36, v44 offset0:2 offset1:18
	v_add_u32_e32 v36, 0xc00, v131
	ds_write2_b32 v36, v37, v45 offset0:3 offset1:19
	ds_write2_b32 v131, v50, v26 offset0:32 offset1:48
	ds_write2_b32 v34, v51, v27 offset0:33 offset1:49
	ds_write2_b32 v35, v52, v28 offset0:34 offset1:50
	ds_write2_b32 v36, v53, v29 offset0:35 offset1:51
	v_add_u32_e32 v26, 0x4000, v131
	ds_write2_b32 v26, v18, v22 offset0:16 offset1:32
	v_add_u32_e32 v18, 0x4400, v131
	ds_write2_b32 v18, v19, v23 offset0:17 offset1:33
	v_add_u32_e32 v19, 0x4800, v131
	ds_write2_b32 v19, v20, v24 offset0:18 offset1:34
	v_add_u32_e32 v20, 0x4c00, v131
	s_waitcnt vmcnt(3)
	v_mfma_f32_16x16x32_bf16 v[66:69], v[102:105], v[78:81], v[66:69]
	s_waitcnt vmcnt(2)
	v_mfma_f32_16x16x32_bf16 v[74:77], v[102:105], v[98:101], v[74:77]
	s_waitcnt vmcnt(1)
	v_mfma_f32_16x16x32_bf16 v[94:97], v[102:105], v[162:165], v[94:97]
	s_waitcnt vmcnt(0)
	v_mfma_f32_16x16x32_bf16 v[58:61], v[102:105], v[166:169], v[58:61]
	v_mfma_f32_16x16x32_bf16 v[46:49], v[158:161], v[78:81], v[46:49]
	v_mfma_f32_16x16x32_bf16 v[54:57], v[158:161], v[98:101], v[54:57]
	v_mfma_f32_16x16x32_bf16 v[70:73], v[158:161], v[162:165], v[70:73]
	v_mfma_f32_16x16x32_bf16 v[62:65], v[158:161], v[166:169], v[62:65]
	ds_write2_b32 v20, v21, v25 offset0:19 offset1:35
	ds_write2_b32 v26, v38, v30 offset0:48 offset1:64
	ds_write2_b32 v18, v39, v31 offset0:49 offset1:65
	ds_write2_b32 v19, v40, v32 offset0:50 offset1:66
	ds_write2_b32 v20, v41, v33 offset0:51 offset1:67
	ds_write2_b32 v131, v66, v74 offset0:128 offset1:144
	ds_write2_b32 v34, v67, v75 offset0:129 offset1:145
	ds_write2_b32 v35, v68, v76 offset0:130 offset1:146
	ds_write2_b32 v36, v69, v77 offset0:131 offset1:147
	ds_write2_b32 v131, v94, v58 offset0:160 offset1:176
	ds_write2_b32 v34, v95, v59 offset0:161 offset1:177
	ds_write2_b32 v35, v96, v60 offset0:162 offset1:178
	ds_write2_b32 v36, v97, v61 offset0:163 offset1:179
	ds_write2_b32 v26, v46, v54 offset0:144 offset1:160
	ds_write2_b32 v18, v47, v55 offset0:145 offset1:161
	ds_write2_b32 v19, v48, v56 offset0:146 offset1:162
	ds_write2_b32 v20, v49, v57 offset0:147 offset1:163
	ds_write2_b32 v26, v70, v62 offset0:176 offset1:192
	ds_write2_b32 v18, v71, v63 offset0:177 offset1:193
	ds_write2_b32 v19, v72, v64 offset0:178 offset1:194
	ds_write2_b32 v20, v73, v65 offset0:179 offset1:195
	v_readfirstlane_b32 s92, v0
	s_nop 3
	s_lshr_b32 s92, s92, 6
	s_and_b32 s88, s92, 6
	s_cmp_eq_u32 s88, 4
	s_cbranch_scc0 .Lmy_cv_pre_done
; DI unsigned enc_key(float s) { const unsigned u = __float_as_uint(s); return (u & 0x80000000u) ? ~u : (u | 0x80000000u); }
; DI void cvt_linear_fp8(const float* __restrict__ src, unsigned char* __restrict__ dst, size_t n16, float scale, size_t gtid, size_t gsz) {
;   for (size_t i = gtid; i < n16; i += gsz) {
;     const float4 a = *(const float4*)(src + i * 16), b = *(const float4*)(src + i * 16 + 4), c = *(const float4*)(src + i * 16 + 8), d = *(const float4*)(src + i * 16 + 12);
; DI void phase_peer_q(const Params& p, char* smem) {
;     ...
;     const int tok = tid & 127, half = (tid >> 7) & 1;
;     if (tid < 256) {
;       const float* srow = Sbuf + tok * 257 + half * 128;
; #pragma unroll
;       for (int i = 0; i < 16; ++i) R[i] = (enc_key(srow[i]) & ~127u) | (unsigned)(127 - i);
	v_mbcnt_lo_u32_b32 v238, -1, 0
	v_mbcnt_hi_u32_b32 v238, -1, v238
	s_sub_u32 s88, s92, 4
	s_lshl_b32 s88, s88, 1
	s_lshl_b32 s93, s77, 2
	s_add_u32 s93, s93, s88
	v_readlane_b32 s100, v239, 12
	v_readlane_b32 s101, v239, 13
	v_lshlrev_b32_e32 v198, 4, v238
	v_lshlrev_b32_e32 v199, 2, v238
	s_mov_b32 s89, s93
	s_lshl_b32 s88, s89, 12
	s_add_u32 s86, s100, s88
	s_addc_u32 s87, s101, 0
	global_load_dwordx4 v[202:205], v198, s[86:87] nt
	global_load_dwordx4 v[206:209], v198, s[86:87] offset:1024 nt
	global_load_dwordx4 v[210:213], v198, s[86:87] offset:2048 nt
	global_load_dwordx4 v[214:217], v198, s[86:87] offset:3072 nt
	s_add_u32 s89, s93, 8192
	s_lshl_b32 s88, s89, 12
	s_add_u32 s86, s100, s88
	s_addc_u32 s87, s101, 0
	global_load_dwordx4 v[240:243], v198, s[86:87] nt
	global_load_dwordx4 v[244:247], v198, s[86:87] offset:1024 nt
	global_load_dwordx4 v[248:251], v198, s[86:87] offset:2048 nt
	global_load_dwordx4 v[252:255], v198, s[86:87] offset:3072 nt
	s_add_u32 s89, s93, 1
	s_lshl_b32 s88, s89, 12
	s_add_u32 s86, s100, s88
	s_addc_u32 s87, s101, 0
	global_load_dwordx4 v[222:225], v198, s[86:87] nt
	global_load_dwordx4 v[226:229], v198, s[86:87] offset:1024 nt
	global_load_dwordx4 v[230:233], v198, s[86:87] offset:2048 nt
	global_load_dwordx4 v[234:237], v198, s[86:87] offset:3072 nt
	s_add_u32 s89, s93, 8193
	s_lshl_b32 s88, s89, 12
	s_add_u32 s86, s100, s88
	s_addc_u32 s87, s101, 0
	global_load_dwordx4 v[186:189], v198, s[86:87] nt
	global_load_dwordx4 v[190:193], v198, s[86:87] offset:1024 nt
	global_load_dwordx4 v[194:197], v198, s[86:87] offset:2048 nt
	global_load_dwordx4 v[218:221], v198, s[86:87] offset:3072 nt
.Lmy_cv_pre_done:
	s_waitcnt lgkmcnt(0)
	s_barrier
	s_and_saveexec_b64 s[62:63], s[6:7]
	s_cbranch_execz .LBB0_407
	ds_read2_b32 v[2:3], v122 offset1:1
	ds_read2_b32 v[4:5], v122 offset0:2 offset1:3
	ds_read2_b32 v[6:7], v122 offset0:4 offset1:5
	ds_read2_b32 v[8:9], v122 offset0:6 offset1:7
	s_movk_i32 s0, 0x60
	s_waitcnt lgkmcnt(3)
	v_not_b32_e32 v10, v2
	v_or_b32_e32 v11, 0x80000000, v2
	v_cmp_gt_i32_e32 vcc, 0, v2
	v_mov_b32_e32 v34, v132
	s_nop 0
	v_cndmask_b32_e32 v2, v11, v10, vcc
	v_or_b32_e32 v10, 0x7f, v2
	v_not_b32_e32 v2, v3
	v_or_b32_e32 v11, 0x80000000, v3
	v_cmp_gt_i32_e32 vcc, 0, v3
	s_waitcnt lgkmcnt(2)
	v_or_b32_e32 v3, 0x80000000, v4
	v_cndmask_b32_e32 v2, v11, v2, vcc
	v_and_b32_e32 v2, 0xffffff80, v2
	v_or_b32_e32 v11, 0x7e, v2
	v_not_b32_e32 v2, v4
	v_cmp_gt_i32_e32 vcc, 0, v4
	s_nop 1
	v_cndmask_b32_e32 v2, v3, v2, vcc
	v_and_b32_e32 v2, 0xffffff80, v2
	v_or_b32_e32 v12, 0x7d, v2
	v_not_b32_e32 v2, v5
	v_or_b32_e32 v3, 0x80000000, v5
	v_cmp_gt_i32_e32 vcc, 0, v5
	s_nop 1
	v_cndmask_b32_e32 v2, v3, v2, vcc
	v_and_b32_e32 v2, 0xffffff80, v2
	v_or_b32_e32 v13, 0x7c, v2
	s_waitcnt lgkmcnt(1)
	v_not_b32_e32 v2, v6
	v_or_b32_e32 v3, 0x80000000, v6
	v_cmp_gt_i32_e32 vcc, 0, v6
	s_nop 1
	v_cndmask_b32_e32 v2, v3, v2, vcc
	v_and_b32_e32 v2, 0xffffff80, v2
	v_or_b32_e32 v14, 0x7b, v2
	v_not_b32_e32 v2, v7
	v_or_b32_e32 v3, 0x80000000, v7
	v_cmp_gt_i32_e32 vcc, 0, v7
	s_nop 1
	v_cndmask_b32_e32 v2, v3, v2, vcc
	v_and_b32_e32 v2, 0xffffff80, v2
	v_or_b32_e32 v15, 0x7a, v2
	s_waitcnt lgkmcnt(0)
	v_not_b32_e32 v2, v8
	v_or_b32_e32 v3, 0x80000000, v8
	v_cmp_gt_i32_e32 vcc, 0, v8
	s_nop 1
	v_cndmask_b32_e32 v2, v3, v2, vcc
	v_and_b32_e32 v2, 0xffffff80, v2
	v_or_b32_e32 v16, 0x79, v2
	v_not_b32_e32 v2, v9
	v_or_b32_e32 v3, 0x80000000, v9
	v_cmp_gt_i32_e32 vcc, 0, v9
	s_nop 1
	v_cndmask_b32_e32 v2, v3, v2, vcc
	v_and_b32_e32 v4, 0xffffff80, v2
	ds_read2_b32 v[2:3], v122 offset0:8 offset1:9
	v_or_b32_e32 v17, 0x78, v4
	ds_read2_b32 v[4:5], v122 offset0:10 offset1:11
	ds_read2_b32 v[6:7], v122 offset0:12 offset1:13
	ds_read2_b32 v[8:9], v122 offset0:14 offset1:15
	s_waitcnt lgkmcnt(3)
	v_not_b32_e32 v18, v2
	v_or_b32_e32 v19, 0x80000000, v2
	v_cmp_gt_i32_e32 vcc, 0, v2
	s_nop 1
	v_cndmask_b32_e32 v2, v19, v18, vcc
	v_not_b32_e32 v18, v3
	v_or_b32_e32 v19, 0x80000000, v3
	v_cmp_gt_i32_e32 vcc, 0, v3
	v_and_b32_e32 v2, 0xffffff80, v2
	v_or_b32_e32 v2, 0x77, v2
	v_cndmask_b32_e32 v3, v19, v18, vcc
	s_waitcnt lgkmcnt(2)
	v_not_b32_e32 v18, v4
	v_or_b32_e32 v19, 0x80000000, v4
	v_cmp_gt_i32_e32 vcc, 0, v4
	v_and_b32_e32 v3, 0xffffff80, v3
	v_or_b32_e32 v3, 0x76, v3
	v_cndmask_b32_e32 v4, v19, v18, vcc
	v_not_b32_e32 v18, v5
	v_or_b32_e32 v19, 0x80000000, v5
	v_cmp_gt_i32_e32 vcc, 0, v5
	v_and_b32_e32 v4, 0xffffff80, v4
	v_or_b32_e32 v4, 0x75, v4
	v_cndmask_b32_e32 v5, v19, v18, vcc
	s_waitcnt lgkmcnt(1)
	v_not_b32_e32 v18, v6
	v_or_b32_e32 v19, 0x80000000, v6
	v_cmp_gt_i32_e32 vcc, 0, v6
	v_and_b32_e32 v5, 0xffffff80, v5
	v_or_b32_e32 v5, 0x74, v5
	v_cndmask_b32_e32 v6, v19, v18, vcc
	v_not_b32_e32 v18, v7
	v_or_b32_e32 v19, 0x80000000, v7
	v_cmp_gt_i32_e32 vcc, 0, v7
	v_and_b32_e32 v6, 0xffffff80, v6
	v_or_b32_e32 v6, 0x73, v6
	v_cndmask_b32_e32 v7, v19, v18, vcc
	s_waitcnt lgkmcnt(0)
; DI void sort16_desc(unsigned (&v)[16]) {
;   constexpr int KS[10] = {2, 4, 4, 8, 8, 8, 16, 16, 16, 16};
;   constexpr int JS[10] = {1, 2, 1, 4, 2, 1, 8, 4, 2, 1};
; #pragma unroll
;   for (int s = 0; s < 10; ++s) {
; #pragma unroll
;     for (int i = 0; i < 16; ++i) {
;       const int l = i ^ JS[s];
;       if (l > i) {
;         if ((i & KS[s]) == 0) cswap(v[i], v[l]); else cswap(v[l], v[i]);
;       }
;     }
;   }
	v_not_b32_e32 v18, v8
	v_or_b32_e32 v19, 0x80000000, v8
	v_cmp_gt_i32_e32 vcc, 0, v8
	v_and_b32_e32 v7, 0xffffff80, v7
	v_or_b32_e32 v7, 0x72, v7
	v_cndmask_b32_e32 v8, v19, v18, vcc
	v_not_b32_e32 v18, v9
	v_or_b32_e32 v19, 0x80000000, v9
	v_cmp_gt_i32_e32 vcc, 0, v9
	v_and_b32_e32 v8, 0xffffff80, v8
	v_or_b32_e32 v8, 0x71, v8
	v_cndmask_b32_e32 v9, v19, v18, vcc
	v_and_b32_e32 v9, 0xffffff80, v9
	v_or_b32_e32 v9, 0x70, v9
	v_max_u32_e32 v18, v10, v11
	v_min_u32_e32 v10, v10, v11
	v_max_u32_e32 v11, v13, v12
	v_min_u32_e32 v12, v13, v12
	v_max_u32_e32 v13, v14, v15
	v_min_u32_e32 v14, v14, v15
	v_max_u32_e32 v15, v17, v16
	v_min_u32_e32 v16, v17, v16
	v_max_u32_e32 v17, v2, v3
	v_min_u32_e32 v2, v2, v3
	v_max_u32_e32 v3, v5, v4
	v_min_u32_e32 v4, v5, v4
	v_max_u32_e32 v5, v6, v7
	v_min_u32_e32 v6, v6, v7
	v_max_u32_e32 v7, v9, v8
	v_min_u32_e32 v8, v9, v8
	v_max_u32_e32 v9, v18, v12
	v_min_u32_e32 v12, v18, v12
	v_max_u32_e32 v18, v10, v11
	v_min_u32_e32 v10, v10, v11
	v_max_u32_e32 v11, v16, v13
	v_min_u32_e32 v13, v16, v13
	v_max_u32_e32 v16, v15, v14
	v_min_u32_e32 v14, v15, v14
	v_max_u32_e32 v15, v17, v4
	v_min_u32_e32 v4, v17, v4
	v_max_u32_e32 v17, v2, v3
	v_min_u32_e32 v2, v2, v3
	v_max_u32_e32 v3, v8, v5
	v_min_u32_e32 v5, v8, v5
	v_max_u32_e32 v8, v7, v6
	v_min_u32_e32 v6, v7, v6
	v_max_u32_e32 v7, v9, v18
	v_min_u32_e32 v9, v9, v18
	v_max_u32_e32 v18, v12, v10
	v_min_u32_e32 v10, v12, v10
	v_max_u32_e32 v12, v14, v13
	v_min_u32_e32 v13, v14, v13
	v_max_u32_e32 v14, v16, v11
	v_min_u32_e32 v11, v16, v11
	v_max_u32_e32 v16, v15, v17
	v_min_u32_e32 v15, v15, v17
	v_max_u32_e32 v17, v4, v2
	v_min_u32_e32 v2, v4, v2
	v_max_u32_e32 v4, v6, v5
	v_min_u32_e32 v5, v6, v5
	v_max_u32_e32 v6, v8, v3
	v_min_u32_e32 v3, v8, v3
	v_max_u32_e32 v8, v7, v13
	v_min_u32_e32 v7, v7, v13
	v_max_u32_e32 v13, v9, v12
	v_min_u32_e32 v9, v9, v12
	v_max_u32_e32 v12, v18, v11
	v_min_u32_e32 v11, v18, v11
	v_max_u32_e32 v18, v10, v14
	v_min_u32_e32 v10, v10, v14
	v_max_u32_e32 v14, v5, v16
	v_min_u32_e32 v5, v5, v16
	v_max_u32_e32 v16, v4, v15
	v_min_u32_e32 v4, v4, v15
	v_max_u32_e32 v15, v3, v17
	v_min_u32_e32 v3, v3, v17
	v_max_u32_e32 v17, v6, v2
	v_min_u32_e32 v2, v6, v2
	v_max_u32_e32 v6, v8, v12
	v_min_u32_e32 v8, v8, v12
	v_max_u32_e32 v12, v13, v18
	v_min_u32_e32 v13, v13, v18
	v_max_u32_e32 v18, v7, v11
	v_min_u32_e32 v7, v7, v11
	v_max_u32_e32 v11, v9, v10
	v_min_u32_e32 v9, v9, v10
	v_max_u32_e32 v10, v3, v5
	v_min_u32_e32 v3, v3, v5
	v_max_u32_e32 v5, v2, v4
	v_min_u32_e32 v2, v2, v4
	v_max_u32_e32 v4, v15, v14
	v_min_u32_e32 v14, v15, v14
	v_max_u32_e32 v15, v17, v16
	v_min_u32_e32 v16, v17, v16
	v_max_u32_e32 v17, v6, v12
	v_min_u32_e32 v6, v6, v12
	v_max_u32_e32 v12, v8, v13
	v_min_u32_e32 v8, v8, v13
	v_max_u32_e32 v13, v18, v11
	v_min_u32_e32 v11, v18, v11
	v_max_u32_e32 v18, v7, v9
	v_min_u32_e32 v7, v7, v9
	v_max_u32_e32 v9, v2, v3
	v_min_u32_e32 v2, v2, v3
	v_max_u32_e32 v3, v5, v10
	v_min_u32_e32 v5, v5, v10
	v_max_u32_e32 v10, v16, v14
	v_min_u32_e32 v14, v16, v14
	v_max_u32_e32 v16, v15, v4
	v_min_u32_e32 v4, v15, v4
	v_max_u32_e32 v15, v17, v2
	v_min_u32_e32 v2, v17, v2
	v_max_u32_e32 v17, v6, v9
	v_min_u32_e32 v6, v6, v9
	v_max_u32_e32 v9, v12, v5
	v_min_u32_e32 v5, v12, v5
	v_max_u32_e32 v12, v8, v3
	v_min_u32_e32 v3, v8, v3
	v_max_u32_e32 v8, v13, v14
	v_min_u32_e32 v13, v13, v14
	v_max_u32_e32 v14, v11, v10
	v_min_u32_e32 v10, v11, v10
	v_max_u32_e32 v11, v18, v4
	v_min_u32_e32 v4, v18, v4
	v_max_u32_e32 v18, v7, v16
	v_min_u32_e32 v7, v7, v16
	v_max_u32_e32 v16, v15, v8
	v_min_u32_e32 v8, v15, v8
	v_max_u32_e32 v15, v17, v14
	v_min_u32_e32 v14, v17, v14
	v_max_u32_e32 v17, v9, v11
	v_min_u32_e32 v9, v9, v11
	v_max_u32_e32 v11, v12, v18
	v_min_u32_e32 v12, v12, v18
	v_max_u32_e32 v18, v2, v13
	v_min_u32_e32 v2, v2, v13
	v_max_u32_e32 v13, v6, v10
	v_min_u32_e32 v6, v6, v10
	v_max_u32_e32 v10, v5, v4
	v_min_u32_e32 v4, v5, v4
	v_max_u32_e32 v5, v3, v7
	v_min_u32_e32 v3, v3, v7
	v_max_u32_e32 v7, v16, v17
	v_min_u32_e32 v16, v16, v17
	v_max_u32_e32 v17, v15, v11
	v_min_u32_e32 v11, v15, v11
	v_max_u32_e32 v15, v8, v9
	v_min_u32_e32 v9, v8, v9
	v_max_u32_e32 v8, v14, v12
	v_min_u32_e32 v12, v14, v12
	v_max_u32_e32 v19, v18, v10
	v_min_u32_e32 v10, v18, v10
	v_max_u32_e32 v18, v13, v5
	v_min_u32_e32 v13, v13, v5
	v_max_u32_e32 v20, v2, v4
	v_min_u32_e32 v21, v2, v4
	v_max_u32_e32 v22, v6, v3
	v_min_u32_e32 v23, v6, v3
	v_max_u32_e32 v2, v7, v17
	v_min_u32_e32 v3, v7, v17
	v_max_u32_e32 v4, v16, v11
	v_min_u32_e32 v5, v16, v11
	v_max_u32_e32 v6, v15, v8
	v_min_u32_e32 v7, v15, v8
	v_max_u32_e32 v8, v9, v12
	v_min_u32_e32 v9, v9, v12
	v_max_u32_e32 v14, v19, v18
	v_min_u32_e32 v15, v19, v18
	v_max_u32_e32 v16, v10, v13
	v_min_u32_e32 v17, v10, v13
	v_max_u32_e32 v10, v20, v22
	v_min_u32_e32 v11, v20, v22
	v_max_u32_e32 v12, v21, v23
	v_min_u32_e32 v13, v21, v23

; DI void cvt_linear_fp8(const float* __restrict__ src, unsigned char* __restrict__ dst, size_t n16, float scale, size_t gtid, size_t gsz) {
;   for (size_t i = gtid; i < n16; i += gsz) {
;     const float4 a = *(const float4*)(src + i * 16), b = *(const float4*)(src + i * 16 + 4), c = *(const float4*)(src + i * 16 + 8), d = *(const float4*)(src + i * 16 + 12);
;     uint4 r;
;     r.x = pk4_fp8(a.x * scale, a.y * scale, a.z * scale, a.w * scale); r.y = pk4_fp8(b.x * scale, b.y * scale, b.z * scale, b.w * scale);
;     r.z = pk4_fp8(c.x * scale, c.y * scale, c.z * scale, c.w * scale); r.w = pk4_fp8(d.x * scale, d.y * scale, d.z * scale, d.w * scale);
;     *(uint4*)(dst + i * 16) = r;
.LBB0_407:
	s_or_b64 exec, exec, s[62:63]
	s_and_b32 s88, s92, 6
	s_cmp_eq_u32 s88, 4
	s_cbranch_scc0 .Lmy_cv_v_done
	s_waitcnt vmcnt(12)
	v_mul_f32_e32 v202, 0x41000000, v202
	v_mul_f32_e32 v203, 0x41000000, v203
	v_mul_f32_e32 v204, 0x41000000, v204
	v_mul_f32_e32 v205, 0x41000000, v205
	v_mul_f32_e32 v206, 0x41000000, v206
	v_mul_f32_e32 v207, 0x41000000, v207
	v_mul_f32_e32 v208, 0x41000000, v208
	v_mul_f32_e32 v209, 0x41000000, v209
	v_mul_f32_e32 v210, 0x41000000, v210
	v_mul_f32_e32 v211, 0x41000000, v211
	v_mul_f32_e32 v212, 0x41000000, v212
	v_mul_f32_e32 v213, 0x41000000, v213
	v_mul_f32_e32 v214, 0x41000000, v214
	v_mul_f32_e32 v215, 0x41000000, v215
	v_mul_f32_e32 v216, 0x41000000, v216
	v_mul_f32_e32 v217, 0x41000000, v217
	v_cvt_pk_fp8_f32 v202, v202, v203
	v_cvt_pk_fp8_f32 v202, v204, v205 op_sel:[0,0,1]
	v_cvt_pk_fp8_f32 v203, v206, v207
	v_cvt_pk_fp8_f32 v203, v208, v209 op_sel:[0,0,1]
	v_cvt_pk_fp8_f32 v204, v210, v211
	v_cvt_pk_fp8_f32 v204, v212, v213 op_sel:[0,0,1]
	v_cvt_pk_fp8_f32 v205, v214, v215
	v_cvt_pk_fp8_f32 v205, v216, v217 op_sel:[0,0,1]
	s_mov_b32 s89, s93
	s_lshl_b32 s88, s89, 10
	s_add_u32 s86, s72, s88
	s_addc_u32 s87, s73, 0
	s_add_u32 s86, s86, 0x6c00000
	s_addc_u32 s87, s87, 0
	global_store_dword v199, v202, s[86:87]
	global_store_dword v199, v203, s[86:87] offset:256
	global_store_dword v199, v204, s[86:87] offset:512
	global_store_dword v199, v205, s[86:87] offset:768
	s_waitcnt vmcnt(12)
	v_mul_f32_e32 v240, 0x41000000, v240
	v_mul_f32_e32 v241, 0x41000000, v241
	v_mul_f32_e32 v242, 0x41000000, v242
	v_mul_f32_e32 v243, 0x41000000, v243
	v_mul_f32_e32 v244, 0x41000000, v244
	v_mul_f32_e32 v245, 0x41000000, v245
	v_mul_f32_e32 v246, 0x41000000, v246
	v_mul_f32_e32 v247, 0x41000000, v247
	v_mul_f32_e32 v248, 0x41000000, v248
	v_mul_f32_e32 v249, 0x41000000, v249
	v_mul_f32_e32 v250, 0x41000000, v250
	v_mul_f32_e32 v251, 0x41000000, v251
	v_mul_f32_e32 v252, 0x41000000, v252
	v_mul_f32_e32 v253, 0x41000000, v253
	v_mul_f32_e32 v254, 0x41000000, v254
	v_mul_f32_e32 v255, 0x41000000, v255
	v_cvt_pk_fp8_f32 v240, v240, v241
	v_cvt_pk_fp8_f32 v240, v242, v243 op_sel:[0,0,1]
	v_cvt_pk_fp8_f32 v241, v244, v245
	v_cvt_pk_fp8_f32 v241, v246, v247 op_sel:[0,0,1]
	v_cvt_pk_fp8_f32 v242, v248, v249
	v_cvt_pk_fp8_f32 v242, v250, v251 op_sel:[0,0,1]
	v_cvt_pk_fp8_f32 v243, v252, v253
	v_cvt_pk_fp8_f32 v243, v254, v255 op_sel:[0,0,1]
	s_add_u32 s89, s93, 8192
	s_lshl_b32 s88, s89, 10
	s_add_u32 s86, s72, s88
	s_addc_u32 s87, s73, 0
	s_add_u32 s86, s86, 0x6c00000
	s_addc_u32 s87, s87, 0
	global_store_dword v199, v240, s[86:87]
	global_store_dword v199, v241, s[86:87] offset:256
	global_store_dword v199, v242, s[86:87] offset:512
	global_store_dword v199, v243, s[86:87] offset:768
	s_waitcnt vmcnt(12)
	v_mul_f32_e32 v222, 0x41000000, v222
	v_mul_f32_e32 v223, 0x41000000, v223
	v_mul_f32_e32 v224, 0x41000000, v224
	v_mul_f32_e32 v225, 0x41000000, v225
	v_mul_f32_e32 v226, 0x41000000, v226
	v_mul_f32_e32 v227, 0x41000000, v227
	v_mul_f32_e32 v228, 0x41000000, v228
	v_mul_f32_e32 v229, 0x41000000, v229
	v_mul_f32_e32 v230, 0x41000000, v230
	v_mul_f32_e32 v231, 0x41000000, v231
	v_mul_f32_e32 v232, 0x41000000, v232
	v_mul_f32_e32 v233, 0x41000000, v233
	v_mul_f32_e32 v234, 0x41000000, v234
	v_mul_f32_e32 v235, 0x41000000, v235
	v_mul_f32_e32 v236, 0x41000000, v236
	v_mul_f32_e32 v237, 0x41000000, v237
	v_cvt_pk_fp8_f32 v222, v222, v223
	v_cvt_pk_fp8_f32 v222, v224, v225 op_sel:[0,0,1]
	v_cvt_pk_fp8_f32 v223, v226, v227
	v_cvt_pk_fp8_f32 v223, v228, v229 op_sel:[0,0,1]
	v_cvt_pk_fp8_f32 v224, v230, v231
	v_cvt_pk_fp8_f32 v224, v232, v233 op_sel:[0,0,1]
	v_cvt_pk_fp8_f32 v225, v234, v235
	v_cvt_pk_fp8_f32 v225, v236, v237 op_sel:[0,0,1]
	s_add_u32 s89, s93, 1
	s_lshl_b32 s88, s89, 10
	s_add_u32 s86, s72, s88
	s_addc_u32 s87, s73, 0
	s_add_u32 s86, s86, 0x6c00000
	s_addc_u32 s87, s87, 0
	global_store_dword v199, v222, s[86:87]
	global_store_dword v199, v223, s[86:87] offset:256
	global_store_dword v199, v224, s[86:87] offset:512
	global_store_dword v199, v225, s[86:87] offset:768
	s_waitcnt vmcnt(12)
	v_mul_f32_e32 v186, 0x41000000, v186
	v_mul_f32_e32 v187, 0x41000000, v187
	v_mul_f32_e32 v188, 0x41000000, v188
	v_mul_f32_e32 v189, 0x41000000, v189
	v_mul_f32_e32 v190, 0x41000000, v190
	v_mul_f32_e32 v191, 0x41000000, v191
	v_mul_f32_e32 v192, 0x41000000, v192
	v_mul_f32_e32 v193, 0x41000000, v193
	v_mul_f32_e32 v194, 0x41000000, v194
	v_mul_f32_e32 v195, 0x41000000, v195
	v_mul_f32_e32 v196, 0x41000000, v196
	v_mul_f32_e32 v197, 0x41000000, v197
	v_mul_f32_e32 v218, 0x41000000, v218
	v_mul_f32_e32 v219, 0x41000000, v219
	v_mul_f32_e32 v220, 0x41000000, v220
	v_mul_f32_e32 v221, 0x41000000, v221
	v_cvt_pk_fp8_f32 v186, v186, v187
	v_cvt_pk_fp8_f32 v186, v188, v189 op_sel:[0,0,1]
	v_cvt_pk_fp8_f32 v187, v190, v191
	v_cvt_pk_fp8_f32 v187, v192, v193 op_sel:[0,0,1]
	v_cvt_pk_fp8_f32 v188, v194, v195
	v_cvt_pk_fp8_f32 v188, v196, v197 op_sel:[0,0,1]
	v_cvt_pk_fp8_f32 v189, v218, v219
	v_cvt_pk_fp8_f32 v189, v220, v221 op_sel:[0,0,1]
	s_add_u32 s89, s93, 8193
	s_lshl_b32 s88, s89, 10
	s_add_u32 s86, s72, s88
	s_addc_u32 s87, s73, 0
	s_add_u32 s86, s86, 0x6c00000
	s_addc_u32 s87, s87, 0
	global_store_dword v199, v186, s[86:87]
	global_store_dword v199, v187, s[86:87] offset:256
	global_store_dword v199, v188, s[86:87] offset:512
	global_store_dword v199, v189, s[86:87] offset:768
; DI void cvt_rows_i8(const float* __restrict__ src, unsigned char* __restrict__ dst, float* __restrict__ scale_out, size_t n16, size_t gtid, size_t gsz) {
;   for (size_t i = gtid; i < n16; i += gsz) {
;     const float4 a = *(const float4*)(src + i * 16), b = *(const float4*)(src + i * 16 + 4), c = *(const float4*)(src + i * 16 + 8), d = *(const float4*)(src + i * 16 + 12);
;     float m = fmaxf(fmaxf(fmaxf(fabsf(a.x), fabsf(a.y)), fmaxf(fabsf(a.z), fabsf(a.w))), fmaxf(fmaxf(fabsf(b.x), fabsf(b.y)), fmaxf(fabsf(b.z), fabsf(b.w))));
;     m = fmaxf(m, fmaxf(fmaxf(fmaxf(fabsf(c.x), fabsf(c.y)), fmaxf(fabsf(c.z), fabsf(c.w))), fmaxf(fmaxf(fabsf(d.x), fabsf(d.y)), fmaxf(fabsf(d.z), fabsf(d.w)))));
; #pragma unroll
;     for (int o = 32; o > 0; o >>= 1) m = fmaxf(m, __shfl_xor(m, o, 64));
;     m = fmaxf(m, 1e-30f);
;     const float q = 127.f / m;
;     uint4 r;
;     r.x = pk4_i8(a.x * q, a.y * q, a.z * q, a.w * q); r.y = pk4_i8(b.x * q, b.y * q, b.z * q, b.w * q);
;     r.z = pk4_i8(c.x * q, c.y * q, c.z * q, c.w * q); r.w = pk4_i8(d.x * q, d.y * q, d.z * q, d.w * q);
;     *(uint4*)(dst + i * 16) = r;
;     if ((i & 63) == 0) scale_out[i >> 6] = m * (1.f / 127.f);
.Lmy_cv_v_done:
	s_waitcnt lgkmcnt(0)
	s_barrier
	s_bitcmp1_b32 s92, 1
	s_cbranch_scc0 .Lmy_cv_u_done
	s_and_b32 s88, s92, 1
	s_lshr_b32 s89, s92, 2
	s_lshl_b32 s89, s89, 1
	s_or_b32 s88, s88, s89
	s_lshl_b32 s93, s77, 2
	s_add_u32 s93, s93, s88
	s_add_u32 s88, s77, s50
	s_waitcnt vmcnt(0)
	v_max_f32_e64 v185, |v205|, |v205|
	v_max_f32_e64 v186, |v204|, |v204|
	v_max_f32_e64 v187, |v209|, |v209|
	v_max_f32_e64 v188, |v208|, |v208|
	v_max_f32_e64 v189, |v211|, |v211|
	v_max_f32_e64 v190, |v210|, |v210|
	v_max_f32_e64 v193, |v217|, |v217|
	v_max_f32_e64 v194, |v216|, |v216|
	v_max_f32_e64 v191, |v213|, |v213|
	v_max_f32_e64 v192, |v212|, |v212|
	v_max_f32_e32 v185, v186, v185
	v_max_f32_e32 v186, v188, v187
	v_max_f32_e32 v187, v190, v189
	v_max_f32_e32 v189, v194, v193
	v_max_f32_e32 v188, v192, v191
	v_max3_f32 v189, |v214|, |v215|, v189
	v_max3_f32 v185, |v202|, |v203|, v185
	v_max3_f32 v186, |v206|, |v207|, v186
	v_max3_f32 v187, v187, v188, v189
	v_max3_f32 v185, v185, v186, v187
	ds_bpermute_b32 v186, v195, v185
	s_waitcnt lgkmcnt(0)
	v_max_f32_e32 v186, v186, v186
	v_max_f32_e32 v185, v185, v186
	ds_bpermute_b32 v186, v196, v185
	s_waitcnt lgkmcnt(0)
	v_max_f32_e32 v186, v186, v186
	v_max_f32_e32 v185, v185, v186
	ds_bpermute_b32 v186, v197, v185
	s_waitcnt lgkmcnt(0)
	v_max_f32_e32 v186, v186, v186
	v_max_f32_e32 v185, v185, v186
	ds_bpermute_b32 v186, v198, v185
	s_waitcnt lgkmcnt(0)
	v_max_f32_e32 v186, v186, v186
	v_max_f32_e32 v185, v185, v186
	ds_bpermute_b32 v186, v199, v185
	s_waitcnt lgkmcnt(0)
	v_max_f32_e32 v186, v186, v186
	v_max_f32_e32 v185, v185, v186
	ds_bpermute_b32 v186, v218, v185
	s_waitcnt lgkmcnt(0)
	v_max3_f32 v185, v185, v186, s96
	v_div_scale_f32 v186, s[94:95], v185, v185, s97
	v_rcp_f32_e32 v187, v186
	v_div_scale_f32 v188, vcc, s97, v185, s97
	v_fma_f32 v189, -v186, v187, 1.0
	v_fmac_f32_e32 v187, v189, v187
	v_mul_f32_e32 v189, v188, v187
	v_fma_f32 v190, -v186, v189, v188
	v_fmac_f32_e32 v189, v190, v187
	v_fma_f32 v186, -v186, v189, v188
	v_div_fmas_f32 v186, v186, v187, v189
	v_div_fixup_f32 v186, v186, v185, s97
	v_mul_f32_e32 v202, v202, v186
	v_mul_f32_e32 v203, v203, v186
	v_mul_f32_e32 v205, v205, v186
	v_mul_f32_e32 v206, v206, v186
	v_mul_f32_e32 v207, v207, v186
	v_mul_f32_e32 v209, v209, v186
	v_mul_f32_e32 v211, v211, v186
	v_mul_f32_e32 v215, v215, v186
	v_mul_f32_e32 v210, v210, v186
	v_mul_f32_e32 v213, v213, v186
	v_mul_f32_e32 v214, v214, v186
	v_mul_f32_e32 v217, v217, v186
	v_rndne_f32_e32 v202, v202
	v_rndne_f32_e32 v203, v203
	v_rndne_f32_e32 v205, v205
	v_rndne_f32_e32 v206, v206
	v_rndne_f32_e32 v207, v207
	v_rndne_f32_e32 v209, v209
	v_rndne_f32_e32 v211, v211
	v_rndne_f32_e32 v215, v215
	v_mul_f32_e32 v204, v204, v186
	v_mul_f32_e32 v208, v208, v186
	v_mul_f32_e32 v212, v212, v186
	v_mul_f32_e32 v216, v216, v186
	v_rndne_f32_e32 v210, v210
	v_rndne_f32_e32 v213, v213
	v_rndne_f32_e32 v214, v214
	v_rndne_f32_e32 v217, v217
	v_cvt_i32_f32_e32 v206, v206
	v_cvt_i32_f32_e32 v202, v202
	v_cvt_i32_f32_e32 v203, v203
	v_cvt_i32_f32_e32 v207, v207
	v_cvt_i32_f32_sdwa v205, v205 dst_sel:BYTE_3 dst_unused:UNUSED_PAD src0_sel:DWORD
	v_cvt_i32_f32_sdwa v209, v209 dst_sel:BYTE_3 dst_unused:UNUSED_PAD src0_sel:DWORD
	v_cvt_i32_f32_e32 v211, v211
	v_cvt_i32_f32_e32 v215, v215
	v_rndne_f32_e32 v204, v204
	v_rndne_f32_e32 v208, v208
	v_rndne_f32_e32 v212, v212
	v_rndne_f32_e32 v216, v216
	v_cvt_i32_f32_e32 v214, v214
	v_cvt_i32_f32_e32 v210, v210
	v_cvt_i32_f32_sdwa v213, v213 dst_sel:BYTE_3 dst_unused:UNUSED_PAD src0_sel:DWORD
	v_cvt_i32_f32_sdwa v217, v217 dst_sel:BYTE_3 dst_unused:UNUSED_PAD src0_sel:DWORD
	v_cvt_i32_f32_sdwa v204, v204 dst_sel:WORD_1 dst_unused:UNUSED_PAD src0_sel:DWORD
	v_cvt_i32_f32_sdwa v208, v208 dst_sel:WORD_1 dst_unused:UNUSED_PAD src0_sel:DWORD
	v_cvt_i32_f32_sdwa v212, v212 dst_sel:WORD_1 dst_unused:UNUSED_PAD src0_sel:DWORD
	v_cvt_i32_f32_sdwa v216, v216 dst_sel:WORD_1 dst_unused:UNUSED_PAD src0_sel:DWORD
	v_lshlrev_b32_e32 v207, 8, v207
	v_lshlrev_b32_e32 v203, 8, v203
	v_or_b32_sdwa v206, v209, v206 dst_sel:DWORD dst_unused:UNUSED_PAD src0_sel:DWORD src1_sel:BYTE_0
	v_or_b32_sdwa v202, v205, v202 dst_sel:DWORD dst_unused:UNUSED_PAD src0_sel:DWORD src1_sel:BYTE_0
	v_lshlrev_b32_e32 v205, 8, v215
	v_lshlrev_b32_e32 v209, 8, v211
	v_or_b32_sdwa v214, v217, v214 dst_sel:DWORD dst_unused:UNUSED_PAD src0_sel:DWORD src1_sel:BYTE_0
	v_or_b32_sdwa v210, v213, v210 dst_sel:DWORD dst_unused:UNUSED_PAD src0_sel:DWORD src1_sel:BYTE_0
	v_and_b32_e32 v207, 0xff00, v207
	v_and_b32_e32 v203, 0xff00, v203
	v_and_b32_e32 v205, 0xff00, v205
	v_and_b32_e32 v209, 0xff00, v209
	v_and_b32_e32 v208, 0xff0000, v208
	v_and_b32_e32 v204, 0xff0000, v204
	v_and_b32_e32 v211, 0xff0000, v216
	v_and_b32_e32 v212, 0xff0000, v212
	v_or_b32_e32 v206, v206, v207
	v_or_b32_e32 v202, v202, v203
	v_or_b32_e32 v205, v214, v205
	v_or_b32_e32 v207, v210, v209
	v_or_b32_e32 v203, v206, v208
	v_or_b32_e32 v202, v202, v204
	v_or_b32_e32 v205, v205, v211
	v_or_b32_e32 v204, v207, v212
	s_mov_b32 s89, s93
	s_lshl_b32 s88, s89, 10
	s_add_u32 s86, s72, s88
	s_addc_u32 s87, s73, 0
	s_add_u32 s86, s86, 0x4c00000
	s_addc_u32 s87, s87, 0
	global_store_dword v220, v202, s[86:87]
	global_store_dword v220, v203, s[86:87] offset:256
	global_store_dword v220, v204, s[86:87] offset:512
	global_store_dword v220, v205, s[86:87] offset:768
	v_mul_f32_e32 v185, 0x3c010204, v185
	s_lshl_b32 s88, s89, 2
	s_add_u32 s86, s72, s88
	s_addc_u32 s87, s73, 0
	s_add_u32 s86, s86, 0x1ec01000
	s_addc_u32 s87, s87, 0
	s_mov_b64 exec, s[90:91]
	global_store_dword v221, v185, s[86:87]
	s_mov_b64 exec, -1
	s_add_u32 s94, s77, s50
	s_cmpk_lt_i32 s94, 0x800
	s_cbranch_scc0 .Lmy_cv_u_nonext0
	s_and_b32 s88, s92, 1
	s_lshr_b32 s89, s92, 2
	s_lshl_b32 s89, s89, 1
	s_or_b32 s88, s88, s89
	s_lshl_b32 s94, s94, 2
	s_add_u32 s94, s94, s88
	s_mov_b32 s89, s94
	s_lshl_b32 s88, s89, 12
	s_add_u32 s86, s98, s88
	s_addc_u32 s87, s99, 0
	global_load_dwordx4 v[202:205], v219, s[86:87] nt
	global_load_dwordx4 v[206:209], v219, s[86:87] offset:1024 nt
	global_load_dwordx4 v[210:213], v219, s[86:87] offset:2048 nt
	global_load_dwordx4 v[214:217], v219, s[86:87] offset:3072 nt
; DI void cvt_rows_i8(const float* __restrict__ src, unsigned char* __restrict__ dst, float* __restrict__ scale_out, size_t n16, size_t gtid, size_t gsz) {
;   for (size_t i = gtid; i < n16; i += gsz) {
;     const float4 a = *(const float4*)(src + i * 16), b = *(const float4*)(src + i * 16 + 4), c = *(const float4*)(src + i * 16 + 8), d = *(const float4*)(src + i * 16 + 12);
;     float m = fmaxf(fmaxf(fmaxf(fabsf(a.x), fabsf(a.y)), fmaxf(fabsf(a.z), fabsf(a.w))), fmaxf(fmaxf(fabsf(b.x), fabsf(b.y)), fmaxf(fabsf(b.z), fabsf(b.w))));
;     m = fmaxf(m, fmaxf(fmaxf(fmaxf(fabsf(c.x), fabsf(c.y)), fmaxf(fabsf(c.z), fabsf(c.w))), fmaxf(fmaxf(fabsf(d.x), fabsf(d.y)), fmaxf(fabsf(d.z), fabsf(d.w)))));
; #pragma unroll
;     for (int o = 32; o > 0; o >>= 1) m = fmaxf(m, __shfl_xor(m, o, 64));
;     m = fmaxf(m, 1e-30f);
;     const float q = 127.f / m;
;     uint4 r;
;     r.x = pk4_i8(a.x * q, a.y * q, a.z * q, a.w * q); r.y = pk4_i8(b.x * q, b.y * q, b.z * q, b.w * q);
;     r.z = pk4_i8(c.x * q, c.y * q, c.z * q, c.w * q); r.w = pk4_i8(d.x * q, d.y * q, d.z * q, d.w * q);
;     *(uint4*)(dst + i * 16) = r;
;     if ((i & 63) == 0) scale_out[i >> 6] = m * (1.f / 127.f);
.Lmy_cv_u_nonext0:
	v_max_f32_e64 v185, |v243|, |v243|
	v_max_f32_e64 v186, |v242|, |v242|
	v_max_f32_e64 v187, |v247|, |v247|
	v_max_f32_e64 v188, |v246|, |v246|
	v_max_f32_e64 v189, |v249|, |v249|
	v_max_f32_e64 v190, |v248|, |v248|
	v_max_f32_e64 v193, |v255|, |v255|
	v_max_f32_e64 v194, |v254|, |v254|
	v_max_f32_e64 v191, |v251|, |v251|
	v_max_f32_e64 v192, |v250|, |v250|
	v_max_f32_e32 v185, v186, v185
	v_max_f32_e32 v186, v188, v187
	v_max_f32_e32 v187, v190, v189
	v_max_f32_e32 v189, v194, v193
	v_max_f32_e32 v188, v192, v191
	v_max3_f32 v189, |v252|, |v253|, v189
	v_max3_f32 v185, |v240|, |v241|, v185
	v_max3_f32 v186, |v244|, |v245|, v186
	v_max3_f32 v187, v187, v188, v189
	v_max3_f32 v185, v185, v186, v187
	ds_bpermute_b32 v186, v195, v185
	s_waitcnt lgkmcnt(0)
	v_max_f32_e32 v186, v186, v186
	v_max_f32_e32 v185, v185, v186
	ds_bpermute_b32 v186, v196, v185
	s_waitcnt lgkmcnt(0)
	v_max_f32_e32 v186, v186, v186
	v_max_f32_e32 v185, v185, v186
	ds_bpermute_b32 v186, v197, v185
	s_waitcnt lgkmcnt(0)
	v_max_f32_e32 v186, v186, v186
	v_max_f32_e32 v185, v185, v186
	ds_bpermute_b32 v186, v198, v185
	s_waitcnt lgkmcnt(0)
	v_max_f32_e32 v186, v186, v186
	v_max_f32_e32 v185, v185, v186
	ds_bpermute_b32 v186, v199, v185
	s_waitcnt lgkmcnt(0)
	v_max_f32_e32 v186, v186, v186
	v_max_f32_e32 v185, v185, v186
	ds_bpermute_b32 v186, v218, v185
	s_waitcnt lgkmcnt(0)
	v_max3_f32 v185, v185, v186, s96
	v_div_scale_f32 v186, s[94:95], v185, v185, s97
	v_rcp_f32_e32 v187, v186
	v_div_scale_f32 v188, vcc, s97, v185, s97
	v_fma_f32 v189, -v186, v187, 1.0
	v_fmac_f32_e32 v187, v189, v187
	v_mul_f32_e32 v189, v188, v187
	v_fma_f32 v190, -v186, v189, v188
	v_fmac_f32_e32 v189, v190, v187
	v_fma_f32 v186, -v186, v189, v188
	v_div_fmas_f32 v186, v186, v187, v189
	v_div_fixup_f32 v186, v186, v185, s97
	v_mul_f32_e32 v240, v240, v186
	v_mul_f32_e32 v241, v241, v186
	v_mul_f32_e32 v243, v243, v186
	v_mul_f32_e32 v244, v244, v186
	v_mul_f32_e32 v245, v245, v186
	v_mul_f32_e32 v247, v247, v186
	v_mul_f32_e32 v249, v249, v186
	v_mul_f32_e32 v253, v253, v186
	v_mul_f32_e32 v248, v248, v186
	v_mul_f32_e32 v251, v251, v186
	v_mul_f32_e32 v252, v252, v186
	v_mul_f32_e32 v255, v255, v186
	v_rndne_f32_e32 v240, v240
	v_rndne_f32_e32 v241, v241
	v_rndne_f32_e32 v243, v243
	v_rndne_f32_e32 v244, v244
	v_rndne_f32_e32 v245, v245
	v_rndne_f32_e32 v247, v247
	v_rndne_f32_e32 v249, v249
	v_rndne_f32_e32 v253, v253
	v_mul_f32_e32 v242, v242, v186
	v_mul_f32_e32 v246, v246, v186
	v_mul_f32_e32 v250, v250, v186
	v_mul_f32_e32 v254, v254, v186
	v_rndne_f32_e32 v248, v248
	v_rndne_f32_e32 v251, v251
	v_rndne_f32_e32 v252, v252
	v_rndne_f32_e32 v255, v255
	v_cvt_i32_f32_e32 v244, v244
	v_cvt_i32_f32_e32 v240, v240
	v_cvt_i32_f32_e32 v241, v241
	v_cvt_i32_f32_e32 v245, v245
	v_cvt_i32_f32_sdwa v243, v243 dst_sel:BYTE_3 dst_unused:UNUSED_PAD src0_sel:DWORD
	v_cvt_i32_f32_sdwa v247, v247 dst_sel:BYTE_3 dst_unused:UNUSED_PAD src0_sel:DWORD
	v_cvt_i32_f32_e32 v249, v249
	v_cvt_i32_f32_e32 v253, v253
	v_rndne_f32_e32 v242, v242
	v_rndne_f32_e32 v246, v246
	v_rndne_f32_e32 v250, v250
	v_rndne_f32_e32 v254, v254
	v_cvt_i32_f32_e32 v252, v252
	v_cvt_i32_f32_e32 v248, v248
	v_cvt_i32_f32_sdwa v251, v251 dst_sel:BYTE_3 dst_unused:UNUSED_PAD src0_sel:DWORD
	v_cvt_i32_f32_sdwa v255, v255 dst_sel:BYTE_3 dst_unused:UNUSED_PAD src0_sel:DWORD
	v_cvt_i32_f32_sdwa v242, v242 dst_sel:WORD_1 dst_unused:UNUSED_PAD src0_sel:DWORD
	v_cvt_i32_f32_sdwa v246, v246 dst_sel:WORD_1 dst_unused:UNUSED_PAD src0_sel:DWORD
	v_cvt_i32_f32_sdwa v250, v250 dst_sel:WORD_1 dst_unused:UNUSED_PAD src0_sel:DWORD
	v_cvt_i32_f32_sdwa v254, v254 dst_sel:WORD_1 dst_unused:UNUSED_PAD src0_sel:DWORD
	v_lshlrev_b32_e32 v245, 8, v245
	v_lshlrev_b32_e32 v241, 8, v241
	v_or_b32_sdwa v244, v247, v244 dst_sel:DWORD dst_unused:UNUSED_PAD src0_sel:DWORD src1_sel:BYTE_0
	v_or_b32_sdwa v240, v243, v240 dst_sel:DWORD dst_unused:UNUSED_PAD src0_sel:DWORD src1_sel:BYTE_0
	v_lshlrev_b32_e32 v243, 8, v253
	v_lshlrev_b32_e32 v247, 8, v249
	v_or_b32_sdwa v252, v255, v252 dst_sel:DWORD dst_unused:UNUSED_PAD src0_sel:DWORD src1_sel:BYTE_0
	v_or_b32_sdwa v248, v251, v248 dst_sel:DWORD dst_unused:UNUSED_PAD src0_sel:DWORD src1_sel:BYTE_0
	v_and_b32_e32 v245, 0xff00, v245
	v_and_b32_e32 v241, 0xff00, v241
	v_and_b32_e32 v243, 0xff00, v243
	v_and_b32_e32 v247, 0xff00, v247
	v_and_b32_e32 v246, 0xff0000, v246
	v_and_b32_e32 v242, 0xff0000, v242
	v_and_b32_e32 v249, 0xff0000, v254
	v_and_b32_e32 v250, 0xff0000, v250
	v_or_b32_e32 v244, v244, v245
	v_or_b32_e32 v240, v240, v241
	v_or_b32_e32 v243, v252, v243
	v_or_b32_e32 v245, v248, v247
	v_or_b32_e32 v241, v244, v246
	v_or_b32_e32 v240, v240, v242
	v_or_b32_e32 v243, v243, v249
	v_or_b32_e32 v242, v245, v250
	s_add_u32 s89, s93, 8192
	s_lshl_b32 s88, s89, 10
	s_add_u32 s86, s72, s88
	s_addc_u32 s87, s73, 0
	s_add_u32 s86, s86, 0x4c00000
	s_addc_u32 s87, s87, 0
	global_store_dword v220, v240, s[86:87]
	global_store_dword v220, v241, s[86:87] offset:256
	global_store_dword v220, v242, s[86:87] offset:512
	global_store_dword v220, v243, s[86:87] offset:768
	v_mul_f32_e32 v185, 0x3c010204, v185
	s_lshl_b32 s88, s89, 2
	s_add_u32 s86, s72, s88
	s_addc_u32 s87, s73, 0
	s_add_u32 s86, s86, 0x1ec01000
	s_addc_u32 s87, s87, 0
	s_mov_b64 exec, s[90:91]
	global_store_dword v221, v185, s[86:87]
	s_mov_b64 exec, -1
	s_add_u32 s94, s77, s50
	s_cmpk_lt_i32 s94, 0x800
	s_cbranch_scc0 .Lmy_cv_u_nonext1
	s_and_b32 s88, s92, 1
	s_lshr_b32 s89, s92, 2
	s_lshl_b32 s89, s89, 1
	s_or_b32 s88, s88, s89
	s_lshl_b32 s94, s94, 2
	s_add_u32 s94, s94, s88
	s_add_u32 s89, s94, 8192
	s_lshl_b32 s88, s89, 12
	s_add_u32 s86, s98, s88
	s_addc_u32 s87, s99, 0
	global_load_dwordx4 v[240:243], v219, s[86:87] nt
	global_load_dwordx4 v[244:247], v219, s[86:87] offset:1024 nt
	global_load_dwordx4 v[248:251], v219, s[86:87] offset:2048 nt
	global_load_dwordx4 v[252:255], v219, s[86:87] offset:3072 nt
; DI unsigned enc_key(float s) { const unsigned u = __float_as_uint(s); return (u & 0x80000000u) ? ~u : (u | 0x80000000u); }
; DI float dec_key(unsigned k) { const unsigned u = (k & 0x80000000u) ? (k & 0x7fffffffu) : ~k; return __uint_as_float(u); }
; DI void phase_peer_q(const Params& p, char* smem) {
;     ...
;     if (tid < 128) {
;       constexpr CandTab CT = make_cands();
;       float s1[16], s2[16];
; #pragma unroll
;       for (int i = 0; i < 16; ++i) { s1[i] = dec_key(R[i] & ~127u); s2[i] = dec_key(xch[(tok * 2 + 1) * 16 + i] & ~127u); }
;       unsigned B[16];
; #pragma unroll
;       for (int gi = 0; gi < 4; ++gi) {
;         unsigned X[16];
; #pragma unroll
;         for (int i = 0; i < 16; ++i) {
;           const int c = gi * 16 + i;
;           X[i] = (c < CT.n) ? ((enc_key(s1[CT.i[c]] + s2[CT.j[c]]) & ~255u) | (unsigned)(255 - (CT.i[c] * 16 + CT.j[c]))) : 0u;
.Lmy_cv_u_nonext1:
.Lmy_cv_u_done:
	s_and_saveexec_b64 s[10:11], s[8:9]
	s_cbranch_execz .LBB0_396
	ds_read_b128 v[22:25], v124 offset:64
	ds_read_b128 v[26:29], v124 offset:80
	ds_read_b128 v[54:57], v124 offset:96
	ds_read_b128 v[18:21], v124 offset:112
	v_and_b32_e32 v30, 0xffffff80, v5
	s_waitcnt lgkmcnt(3)
	v_and_b32_e32 v31, 0xffffff80, v25
	v_and_b32_e32 v32, 0x7fffff80, v25
	v_xor_b32_e32 v31, -1, v31
	v_cmp_gt_i32_e32 vcc, 0, v25
	v_and_b32_e32 v33, 0x7fffff80, v5
	v_xor_b32_e32 v30, -1, v30
	v_cndmask_b32_e32 v34, v31, v32, vcc
	v_cmp_gt_i32_e32 vcc, 0, v5
	v_and_b32_e32 v25, 0xffffff80, v24
	v_and_b32_e32 v31, 0x7fffff80, v24
	v_cndmask_b32_e32 v36, v30, v33, vcc
	v_and_b32_e32 v30, 0xffffff80, v6
	v_xor_b32_e32 v25, -1, v25
	v_cmp_gt_i32_e32 vcc, 0, v24
	v_and_b32_e32 v32, 0x7fffff80, v6
	v_xor_b32_e32 v30, -1, v30
	v_cndmask_b32_e32 v35, v25, v31, vcc
	v_cmp_gt_i32_e32 vcc, 0, v6
	s_waitcnt lgkmcnt(2)
	v_and_b32_e32 v24, 0xffffff80, v26
	v_and_b32_e32 v25, 0xffffff80, v4
	v_cndmask_b32_e32 v30, v30, v32, vcc
	v_and_b32_e32 v31, 0x7fffff80, v26
	v_xor_b32_e32 v24, -1, v24
	v_cmp_gt_i32_e32 vcc, 0, v26
	v_and_b32_e32 v32, 0x7fffff80, v4
	v_xor_b32_e32 v25, -1, v25
	v_cndmask_b32_e32 v39, v24, v31, vcc
	v_cmp_gt_i32_e32 vcc, 0, v4
	v_and_b32_e32 v24, 0x7fffff80, v7
	v_and_b32_e32 v31, 0x7fffff80, v3
	v_cndmask_b32_e32 v40, v25, v32, vcc
	v_bitop3_b32 v25, v7, s67, v7 bitop3:0xcf
	v_cmp_gt_i32_e32 vcc, 0, v7
	v_and_b32_e32 v37, 0x7fffff80, v12
	s_waitcnt lgkmcnt(1)
	v_and_b32_e32 v66, 0x7fffff80, v55
	v_cndmask_b32_e32 v32, v25, v24, vcc
	v_and_b32_e32 v24, 0x7fffff80, v27
	v_bitop3_b32 v25, v27, s67, v27 bitop3:0xcf
	v_cmp_gt_i32_e32 vcc, 0, v27
	v_and_b32_e32 v27, 0x7fffff80, v23
	v_and_b32_e32 v67, 0x7fffff80, v54
	v_cndmask_b32_e32 v38, v25, v24, vcc
	v_and_b32_e32 v24, 0x7fffff80, v8
	v_bitop3_b32 v25, v8, s67, v8 bitop3:0xcf
	v_cmp_gt_i32_e32 vcc, 0, v8
	v_and_b32_e32 v45, 0xffffff80, v17
	v_and_b32_e32 v41, 0x7fffff80, v11
	v_cndmask_b32_e32 v26, v25, v24, vcc
	v_and_b32_e32 v24, 0x7fffff80, v28
	v_bitop3_b32 v25, v28, s67, v28 bitop3:0xcf
	v_cmp_gt_i32_e32 vcc, 0, v28
	v_and_b32_e32 v28, 0x7fffff80, v9
	v_and_b32_e32 v33, 0x7fffff80, v10
	v_cndmask_b32_e32 v43, v25, v24, vcc
	v_and_b32_e32 v24, 0xffffff80, v23
	v_and_b32_e32 v25, 0xffffff80, v9
	v_xor_b32_e32 v24, -1, v24
	v_cmp_gt_i32_e32 vcc, 0, v23
	v_xor_b32_e32 v25, -1, v25
	v_and_b32_e32 v23, 0xffffff80, v29
	v_cndmask_b32_e32 v24, v24, v27, vcc
	v_cmp_gt_i32_e32 vcc, 0, v9
	v_and_b32_e32 v27, 0x7fffff80, v29
	v_xor_b32_e32 v23, -1, v23
	v_cndmask_b32_e32 v28, v25, v28, vcc
	v_and_b32_e32 v25, 0xffffff80, v3
	v_xor_b32_e32 v25, -1, v25
	v_cmp_gt_i32_e32 vcc, 0, v3
	v_and_b32_e32 v49, 0xffffff80, v15
	v_and_b32_e32 v50, 0xffffff80, v14
	v_cndmask_b32_e32 v44, v25, v31, vcc
	v_cmp_gt_i32_e32 vcc, 0, v29
	v_and_b32_e32 v25, 0xffffff80, v12
	v_and_b32_e32 v31, 0x7fffff80, v22
	v_cndmask_b32_e32 v42, v23, v27, vcc
	v_and_b32_e32 v23, 0xffffff80, v22
	v_xor_b32_e32 v23, -1, v23
	v_cmp_gt_i32_e32 vcc, 0, v22
	v_xor_b32_e32 v53, -1, v25
	s_waitcnt lgkmcnt(0)
	v_and_b32_e32 v22, 0x7fffff80, v20
	v_cndmask_b32_e32 v25, v23, v31, vcc
	v_cmp_gt_i32_e32 vcc, 0, v12
	v_bitop3_b32 v31, v20, s67, v20 bitop3:0xcf
	v_and_b32_e32 v27, 0xffffff80, v11
	v_cndmask_b32_e32 v23, v53, v37, vcc
	v_cmp_gt_i32_e32 vcc, 0, v20
	v_and_b32_e32 v20, 0x7fffff80, v13
	v_and_b32_e32 v37, 0x7fffff80, v21
	v_cndmask_b32_e32 v59, v31, v22, vcc
	v_bitop3_b32 v22, v13, s67, v13 bitop3:0xcf
	v_cmp_gt_i32_e32 vcc, 0, v13
	v_and_b32_e32 v31, 0xffffff80, v2
	v_and_b32_e32 v53, 0x7fffff80, v2
	v_cndmask_b32_e32 v22, v22, v20, vcc
	v_and_b32_e32 v20, 0xffffff80, v21
	v_xor_b32_e32 v20, -1, v20
	v_cmp_gt_i32_e32 vcc, 0, v21
	v_xor_b32_e32 v31, -1, v31
	v_and_b32_e32 v29, 0xffffff80, v10
	v_cndmask_b32_e32 v58, v20, v37, vcc
	v_cmp_gt_i32_e32 vcc, 0, v2
	v_and_b32_e32 v52, 0x7fffff80, v15
	v_and_b32_e32 v51, 0x7fffff80, v14
	v_cndmask_b32_e32 v20, v31, v53, vcc
	v_pk_add_f32 v[60:61], v[20:21], v[24:25] op_sel_hi:[0,1]
	v_not_b32_e32 v21, v61
	v_or_b32_e32 v31, 0x80000000, v61
	v_cmp_gt_i32_e32 vcc, 0, v61
	v_or_b32_e32 v37, 0x80000000, v60
	v_and_b32_e32 v46, 0xffffff80, v16
	v_cndmask_b32_e32 v21, v31, v21, vcc
	v_or_b32_e32 v21, 0xff, v21
	v_not_b32_e32 v31, v60
	v_cmp_gt_i32_e32 vcc, 0, v60
	v_pk_add_f32 v[60:61], v[20:21], v[34:35] op_sel_hi:[0,1]
	v_or_b32_e32 v53, 0x80000000, v61
	v_cndmask_b32_e32 v31, v37, v31, vcc
	v_not_b32_e32 v37, v61
	v_cmp_gt_i32_e32 vcc, 0, v61
	v_or_b32_e32 v61, 0x80000000, v60
	v_and_b32_e32 v31, 0xffffff00, v31
	v_cndmask_b32_e32 v37, v53, v37, vcc
	v_not_b32_e32 v53, v60
	v_cmp_gt_i32_e32 vcc, 0, v60
	v_and_b32_e32 v37, 0xffffff00, v37
	v_or_b32_e32 v31, 0xfe, v31
	v_cndmask_b32_e32 v53, v61, v53, vcc
	v_pk_add_f32 v[60:61], v[20:21], v[38:39] op_sel_hi:[0,1]
	v_not_b32_e32 v62, v61
	v_or_b32_e32 v63, 0x80000000, v61
	v_cmp_gt_i32_e32 vcc, 0, v61
	v_and_b32_e32 v53, 0xffffff00, v53
	v_or_b32_e32 v37, 0xfd, v37
	v_cndmask_b32_e32 v61, v63, v62, vcc
	v_and_b32_e32 v61, 0xffffff00, v61
	v_or_b32_e32 v62, 0xfb, v61
	v_not_b32_e32 v61, v60
	v_or_b32_e32 v63, 0x80000000, v60
	v_cmp_gt_i32_e32 vcc, 0, v60
	v_or_b32_e32 v53, 0xfc, v53
	v_and_b32_e32 v48, 0x7fffff80, v17
	v_cndmask_b32_e32 v60, v63, v61, vcc
	v_and_b32_e32 v60, 0xffffff00, v60
	v_or_b32_e32 v63, 0xfa, v60
	v_pk_add_f32 v[60:61], v[20:21], v[42:43] op_sel_hi:[0,1]
	v_not_b32_e32 v64, v61
	v_or_b32_e32 v65, 0x80000000, v61
	v_cmp_gt_i32_e32 vcc, 0, v61
	v_and_b32_e32 v47, 0x7fffff80, v16
	s_nop 0
	v_cndmask_b32_e32 v61, v65, v64, vcc
	v_not_b32_e32 v64, v60
	v_or_b32_e32 v65, 0x80000000, v60
	v_cmp_gt_i32_e32 vcc, 0, v60
; DI unsigned enc_key(float s) { const unsigned u = __float_as_uint(s); return (u & 0x80000000u) ? ~u : (u | 0x80000000u); }
; DI void phase_peer_q(const Params& p, char* smem) {
;     ...
;       for (int gi = 0; gi < 4; ++gi) {
;         unsigned X[16];
; #pragma unroll
;         for (int i = 0; i < 16; ++i) {
;           const int c = gi * 16 + i;
;           X[i] = (c < CT.n) ? ((enc_key(s1[CT.i[c]] + s2[CT.j[c]]) & ~255u) | (unsigned)(255 - (CT.i[c] * 16 + CT.j[c]))) : 0u;
;         }
;         sort16_desc(X);
;         if (gi == 0) {
; #pragma unroll
;           for (int i = 0; i < 16; ++i) B[i] = X[i];
;         } else merge16_desc(B, X);
;       }
	v_and_b32_e32 v61, 0xffffff00, v61
	v_or_b32_e32 v61, 0xf9, v61
	v_cndmask_b32_e32 v60, v65, v64, vcc
	v_and_b32_e32 v64, 0xffffff80, v55
	v_and_b32_e32 v65, 0xffffff80, v54
	v_xor_b32_e32 v64, -1, v64
	v_cmp_gt_i32_e32 vcc, 0, v55
	v_xor_b32_e32 v65, -1, v65
	v_and_b32_e32 v60, 0xffffff00, v60
	v_cndmask_b32_e32 v55, v64, v66, vcc
	v_cmp_gt_i32_e32 vcc, 0, v54
	v_and_b32_e32 v66, 0x7fffff80, v57
	v_or_b32_e32 v60, 0xf8, v60
	v_cndmask_b32_e32 v54, v65, v67, vcc
	v_pk_add_f32 v[54:55], v[20:21], v[54:55] op_sel_hi:[0,1]
	v_not_b32_e32 v64, v54
	v_or_b32_e32 v65, 0x80000000, v54
	v_cmp_gt_i32_e32 vcc, 0, v54
	v_and_b32_e32 v67, 0x7fffff80, v56
	s_nop 0
	v_cndmask_b32_e32 v54, v65, v64, vcc
	v_and_b32_e32 v54, 0xffffff00, v54
	v_or_b32_e32 v64, 0xf7, v54
	v_not_b32_e32 v54, v55
	v_or_b32_e32 v65, 0x80000000, v55
	v_cmp_gt_i32_e32 vcc, 0, v55
	v_and_b32_e32 v55, 0xffffff80, v56
	v_xor_b32_e32 v68, -1, v55
	v_cndmask_b32_e32 v54, v65, v54, vcc
	v_and_b32_e32 v54, 0xffffff00, v54
	v_or_b32_e32 v65, 0xf6, v54
	v_and_b32_e32 v54, 0xffffff80, v57
	v_xor_b32_e32 v54, -1, v54
	v_cmp_gt_i32_e32 vcc, 0, v57
	s_nop 1
	v_cndmask_b32_e32 v55, v54, v66, vcc
	v_cmp_gt_i32_e32 vcc, 0, v56
	v_and_b32_e32 v66, 0x7fffff80, v19
	s_nop 0
	v_cndmask_b32_e32 v54, v68, v67, vcc
	v_pk_add_f32 v[54:55], v[20:21], v[54:55] op_sel_hi:[0,1]
	v_not_b32_e32 v56, v54
	v_or_b32_e32 v57, 0x80000000, v54
	v_cmp_gt_i32_e32 vcc, 0, v54
	v_and_b32_e32 v67, 0x7fffff80, v18
	s_nop 0
	v_cndmask_b32_e32 v54, v57, v56, vcc
	v_not_b32_e32 v56, v55
	v_or_b32_e32 v57, 0x80000000, v55
	v_cmp_gt_i32_e32 vcc, 0, v55
	v_and_b32_e32 v54, 0xffffff00, v54
	v_or_b32_e32 v54, 0xf5, v54
	v_cndmask_b32_e32 v55, v57, v56, vcc
	v_and_b32_e32 v56, 0xffffff80, v19
	v_and_b32_e32 v57, 0xffffff80, v18
	v_xor_b32_e32 v56, -1, v56
	v_cmp_gt_i32_e32 vcc, 0, v19
	v_xor_b32_e32 v57, -1, v57
	v_and_b32_e32 v55, 0xffffff00, v55
	v_cndmask_b32_e32 v19, v56, v66, vcc
	v_cmp_gt_i32_e32 vcc, 0, v18
	v_or_b32_e32 v55, 0xf4, v55
	s_nop 0
	v_cndmask_b32_e32 v18, v57, v67, vcc
	v_pk_add_f32 v[18:19], v[20:21], v[18:19] op_sel_hi:[0,1]
	v_not_b32_e32 v56, v18
	v_or_b32_e32 v57, 0x80000000, v18
	v_cmp_gt_i32_e32 vcc, 0, v18
	s_nop 1
	v_cndmask_b32_e32 v18, v57, v56, vcc
	v_and_b32_e32 v18, 0xffffff00, v18
	v_or_b32_e32 v56, 0xf3, v18
	v_not_b32_e32 v18, v19
	v_or_b32_e32 v57, 0x80000000, v19
	v_cmp_gt_i32_e32 vcc, 0, v19
	s_nop 1
	v_cndmask_b32_e32 v18, v57, v18, vcc
	v_and_b32_e32 v18, 0xffffff00, v18
	v_or_b32_e32 v57, 0xf2, v18
	v_pk_add_f32 v[18:19], v[20:21], v[58:59] op_sel_hi:[0,1]
	v_not_b32_e32 v20, v19
	v_or_b32_e32 v58, 0x80000000, v19
	v_cmp_gt_i32_e32 vcc, 0, v19
	v_max_u32_e32 v59, v60, v61
	v_min_u32_e32 v60, v60, v61
	v_cndmask_b32_e32 v19, v58, v20, vcc
	v_not_b32_e32 v20, v18
	v_or_b32_e32 v58, 0x80000000, v18
	v_cmp_gt_i32_e32 vcc, 0, v18
	v_and_b32_e32 v19, 0xffffff00, v19
	v_or_b32_e32 v19, 0xf1, v19
	v_cndmask_b32_e32 v18, v58, v20, vcc
	v_and_b32_e32 v18, 0xffffff00, v18
	v_or_b32_e32 v18, 0xf0, v18
	v_max_u32_e32 v20, v21, v31
	v_min_u32_e32 v21, v21, v31
	v_max_u32_e32 v31, v53, v37
	v_min_u32_e32 v37, v53, v37
	v_max_u32_e32 v53, v62, v63
	v_min_u32_e32 v58, v62, v63
	v_max_u32_e32 v61, v64, v65
	v_min_u32_e32 v62, v64, v65
	v_max_u32_e32 v63, v55, v54
	v_min_u32_e32 v54, v55, v54
	v_max_u32_e32 v55, v56, v57
	v_min_u32_e32 v56, v56, v57
	v_max_u32_e32 v57, v18, v19
	v_min_u32_e32 v18, v18, v19
	v_max_u32_e32 v19, v20, v37
	v_min_u32_e32 v20, v20, v37
	v_max_u32_e32 v37, v21, v31
	v_min_u32_e32 v21, v21, v31
	v_max_u32_e32 v31, v60, v53
	v_min_u32_e32 v53, v60, v53
	v_max_u32_e32 v60, v59, v58
	v_min_u32_e32 v58, v59, v58
	v_max_u32_e32 v59, v61, v54
	v_min_u32_e32 v54, v61, v54
	v_max_u32_e32 v61, v62, v63
	v_min_u32_e32 v62, v62, v63
	v_max_u32_e32 v63, v18, v55
	v_min_u32_e32 v18, v18, v55
	v_max_u32_e32 v55, v57, v56
	v_min_u32_e32 v56, v57, v56
	v_max_u32_e32 v57, v19, v37
	v_min_u32_e32 v19, v19, v37
	v_max_u32_e32 v37, v20, v21
	v_min_u32_e32 v20, v20, v21
	v_max_u32_e32 v21, v58, v53
	v_min_u32_e32 v53, v58, v53
	v_max_u32_e32 v58, v60, v31
	v_min_u32_e32 v31, v60, v31
	v_max_u32_e32 v60, v59, v61
	v_min_u32_e32 v59, v59, v61
	v_max_u32_e32 v61, v54, v62
	v_min_u32_e32 v54, v54, v62
	v_max_u32_e32 v62, v56, v18
	v_min_u32_e32 v18, v56, v18
	v_max_u32_e32 v56, v55, v63
	v_min_u32_e32 v55, v55, v63
	v_max_u32_e32 v63, v57, v53
	v_min_u32_e32 v53, v57, v53
	v_max_u32_e32 v57, v19, v21
	v_min_u32_e32 v19, v19, v21
	v_max_u32_e32 v21, v37, v31
	v_min_u32_e32 v31, v37, v31
	v_max_u32_e32 v37, v20, v58
	v_min_u32_e32 v20, v20, v58
	v_max_u32_e32 v58, v18, v60
	v_min_u32_e32 v18, v18, v60
	v_max_u32_e32 v60, v62, v59
	v_min_u32_e32 v59, v62, v59
	v_max_u32_e32 v62, v55, v61
	v_min_u32_e32 v55, v55, v61
	v_max_u32_e32 v61, v56, v54
	v_min_u32_e32 v54, v56, v54
	v_max_u32_e32 v56, v63, v21
	v_min_u32_e32 v21, v63, v21
	v_max_u32_e32 v63, v57, v37
	v_min_u32_e32 v37, v57, v37
	v_max_u32_e32 v57, v53, v31
	v_min_u32_e32 v31, v53, v31
	v_max_u32_e32 v53, v19, v20
	v_min_u32_e32 v19, v19, v20
	v_max_u32_e32 v20, v55, v18
	v_min_u32_e32 v18, v55, v18
	v_max_u32_e32 v55, v54, v59
	v_min_u32_e32 v54, v54, v59
	v_max_u32_e32 v59, v62, v58
	v_min_u32_e32 v58, v62, v58
	v_max_u32_e32 v62, v61, v60
	v_min_u32_e32 v60, v61, v60
	v_max_u32_e32 v61, v56, v63
	v_min_u32_e32 v56, v56, v63
	v_max_u32_e32 v63, v21, v37
	v_min_u32_e32 v21, v21, v37
	v_max_u32_e32 v37, v57, v53
	v_min_u32_e32 v53, v57, v53
	v_max_u32_e32 v57, v31, v19
	v_min_u32_e32 v19, v31, v19
	v_max_u32_e32 v31, v54, v18
	v_min_u32_e32 v18, v54, v18
	v_max_u32_e32 v54, v55, v20
	v_min_u32_e32 v20, v55, v20
	v_max_u32_e32 v55, v60, v58
; DI unsigned enc_key(float s) { const unsigned u = __float_as_uint(s); return (u & 0x80000000u) ? ~u : (u | 0x80000000u); }
; DI void phase_peer_q(const Params& p, char* smem) {
;     ...
;       for (int gi = 0; gi < 4; ++gi) {
;         unsigned X[16];
; #pragma unroll
;         for (int i = 0; i < 16; ++i) {
;           const int c = gi * 16 + i;
;           X[i] = (c < CT.n) ? ((enc_key(s1[CT.i[c]] + s2[CT.j[c]]) & ~255u) | (unsigned)(255 - (CT.i[c] * 16 + CT.j[c]))) : 0u;
;         }
;         sort16_desc(X);
;         if (gi == 0) {
; #pragma unroll
;           for (int i = 0; i < 16; ++i) B[i] = X[i];
;         } else merge16_desc(B, X);
;       }
	v_min_u32_e32 v58, v60, v58
	v_max_u32_e32 v60, v62, v59
	v_min_u32_e32 v59, v62, v59
	v_max_u32_e32 v62, v61, v18
	v_min_u32_e32 v18, v61, v18
	v_max_u32_e32 v61, v56, v31
	v_min_u32_e32 v31, v56, v31
	v_max_u32_e32 v56, v63, v20
	v_min_u32_e32 v20, v63, v20
	v_max_u32_e32 v63, v21, v54
	v_min_u32_e32 v21, v21, v54
	v_max_u32_e32 v54, v37, v58
	v_min_u32_e32 v37, v37, v58
	v_max_u32_e32 v58, v53, v55
	v_min_u32_e32 v53, v53, v55
	v_max_u32_e32 v55, v57, v59
	v_min_u32_e32 v57, v57, v59
	v_max_u32_e32 v59, v19, v60
	v_min_u32_e32 v19, v19, v60
	v_max_u32_e32 v60, v62, v54
	v_min_u32_e32 v54, v62, v54
	v_max_u32_e32 v62, v61, v58
	v_min_u32_e32 v58, v61, v58
	v_max_u32_e32 v61, v56, v55
	v_min_u32_e32 v55, v56, v55
	v_max_u32_e32 v56, v63, v59
	v_min_u32_e32 v59, v63, v59
	v_max_u32_e32 v63, v18, v37
	v_min_u32_e32 v18, v18, v37
	v_max_u32_e32 v37, v31, v53
	v_min_u32_e32 v31, v31, v53
	v_max_u32_e32 v53, v20, v57
	v_min_u32_e32 v20, v20, v57
	v_max_u32_e32 v57, v21, v19
	v_min_u32_e32 v19, v21, v19
	v_max_u32_e32 v65, v18, v20
	v_min_u32_e32 v66, v18, v20
	v_max_u32_e32 v67, v31, v19
	v_min_u32_e32 v31, v31, v19
	v_pk_add_f32 v[18:19], v[44:45], v[24:25] op_sel_hi:[0,1]
	v_not_b32_e32 v20, v19
	v_or_b32_e32 v21, 0x80000000, v19
	v_cmp_gt_i32_e32 vcc, 0, v19
	v_max_u32_e32 v64, v60, v61
	v_min_u32_e32 v60, v60, v61
	v_cndmask_b32_e32 v19, v21, v20, vcc
	v_and_b32_e32 v19, 0xffffff00, v19
	v_or_b32_e32 v20, 0xef, v19
	v_not_b32_e32 v19, v18
	v_or_b32_e32 v21, 0x80000000, v18
	v_cmp_gt_i32_e32 vcc, 0, v18
	v_max_u32_e32 v61, v62, v56
	v_min_u32_e32 v56, v62, v56
	v_cndmask_b32_e32 v18, v21, v19, vcc
	v_and_b32_e32 v18, 0xffffff00, v18
	v_or_b32_e32 v21, 0xee, v18
	v_pk_add_f32 v[18:19], v[44:45], v[34:35] op_sel_hi:[0,1]
	v_max_u32_e32 v62, v54, v55
	v_min_u32_e32 v54, v54, v55
	v_max_u32_e32 v55, v58, v59
	v_min_u32_e32 v58, v58, v59
	v_max_u32_e32 v59, v63, v53
	v_min_u32_e32 v53, v63, v53
	v_max_u32_e32 v63, v37, v57
	v_min_u32_e32 v57, v37, v57
	v_not_b32_e32 v37, v19
	v_or_b32_e32 v76, 0x80000000, v19
	v_cmp_gt_i32_e32 vcc, 0, v19
	v_min_u32_e32 v68, v64, v61
	v_min_u32_e32 v69, v60, v56
	v_cndmask_b32_e32 v19, v76, v37, vcc
	v_and_b32_e32 v19, 0xffffff00, v19
	v_or_b32_e32 v76, 0xed, v19
	v_not_b32_e32 v19, v18
	v_or_b32_e32 v37, 0x80000000, v18
	v_cmp_gt_i32_e32 vcc, 0, v18
	v_min_u32_e32 v70, v62, v55
	v_min_u32_e32 v71, v54, v58
	v_cndmask_b32_e32 v18, v37, v19, vcc
	v_and_b32_e32 v18, 0xffffff00, v18
	v_or_b32_e32 v77, 0xec, v18
	v_pk_add_f32 v[18:19], v[44:45], v[38:39] op_sel_hi:[0,1]
	v_not_b32_e32 v37, v19
	v_or_b32_e32 v38, 0x80000000, v19
	v_cmp_gt_i32_e32 vcc, 0, v19
	v_min_u32_e32 v72, v59, v63
	v_min_u32_e32 v73, v53, v57
	v_cndmask_b32_e32 v19, v38, v37, vcc
	v_and_b32_e32 v19, 0xffffff00, v19
	v_or_b32_e32 v78, 0xeb, v19
	v_not_b32_e32 v19, v18
	v_or_b32_e32 v37, 0x80000000, v18
	v_cmp_gt_i32_e32 vcc, 0, v18
	v_min_u32_e32 v74, v65, v67
	v_min_u32_e32 v75, v66, v31
	v_cndmask_b32_e32 v18, v37, v19, vcc
	v_and_b32_e32 v18, 0xffffff00, v18
	v_or_b32_e32 v79, 0xea, v18
	v_pk_add_f32 v[18:19], v[44:45], v[42:43] op_sel_hi:[0,1]
	v_not_b32_e32 v37, v19
	v_or_b32_e32 v38, 0x80000000, v19
	v_cmp_gt_i32_e32 vcc, 0, v19
	v_min_u32_e32 v95, v78, v79
	s_nop 0
	v_cndmask_b32_e32 v19, v38, v37, vcc
	v_and_b32_e32 v19, 0xffffff00, v19
	v_or_b32_e32 v42, 0xe9, v19
	v_not_b32_e32 v19, v18
	v_or_b32_e32 v37, 0x80000000, v18
	v_cmp_gt_i32_e32 vcc, 0, v18
	s_nop 1
	v_cndmask_b32_e32 v18, v37, v19, vcc
	v_and_b32_e32 v18, 0xffffff00, v18
	v_or_b32_e32 v43, 0xe8, v18
	v_pk_add_f32 v[18:19], v[40:41], v[24:25] op_sel_hi:[0,1]
	v_not_b32_e32 v37, v19
	v_or_b32_e32 v38, 0x80000000, v19
	v_cmp_gt_i32_e32 vcc, 0, v19
	s_nop 1
	v_cndmask_b32_e32 v19, v38, v37, vcc
	v_and_b32_e32 v19, 0xffffff00, v19
	v_or_b32_e32 v44, 0xdf, v19
	v_not_b32_e32 v19, v18
	v_or_b32_e32 v37, 0x80000000, v18
	v_cmp_gt_i32_e32 vcc, 0, v18
	s_nop 1
	v_cndmask_b32_e32 v18, v37, v19, vcc
	v_and_b32_e32 v18, 0xffffff00, v18
	v_or_b32_e32 v80, 0xde, v18
	v_pk_add_f32 v[18:19], v[40:41], v[34:35] op_sel_hi:[0,1]
	v_not_b32_e32 v37, v19
	v_or_b32_e32 v38, 0x80000000, v19
	v_cmp_gt_i32_e32 vcc, 0, v19
	v_max_u32_e32 v104, v44, v80
	v_min_u32_e32 v44, v44, v80
	v_cndmask_b32_e32 v19, v38, v37, vcc
	v_and_b32_e32 v19, 0xffffff00, v19
	v_or_b32_e32 v81, 0xdd, v19
	v_not_b32_e32 v19, v18
	v_or_b32_e32 v37, 0x80000000, v18
	v_cmp_gt_i32_e32 vcc, 0, v18
	v_mov_b32_e32 v38, v25
	s_nop 0
	v_cndmask_b32_e32 v18, v37, v19, vcc
	v_and_b32_e32 v18, 0xffffff00, v18
	v_mov_b32_e32 v37, v40
	v_or_b32_e32 v94, 0xdc, v18
	v_pk_add_f32 v[18:19], v[36:37], v[38:39]
	v_min_u32_e32 v105, v94, v81
	v_not_b32_e32 v37, v19
	v_or_b32_e32 v38, 0x80000000, v19
	v_cmp_gt_i32_e32 vcc, 0, v19
	v_max_u32_e32 v80, v94, v81
	v_min_u32_e32 v157, v104, v105
	v_cndmask_b32_e32 v19, v38, v37, vcc
	v_and_b32_e32 v19, 0xffffff00, v19
	v_or_b32_e32 v37, 0xdb, v19
	v_not_b32_e32 v19, v18
	v_or_b32_e32 v38, 0x80000000, v18
	v_cmp_gt_i32_e32 vcc, 0, v18
	v_min_u32_e32 v81, v44, v80
	v_max_u32_e32 v44, v44, v80
	v_cndmask_b32_e32 v18, v38, v19, vcc
	v_and_b32_e32 v18, 0xffffff00, v18
	v_or_b32_e32 v38, 0xcf, v18
	v_max_u32_e32 v18, v20, v21
	v_min_u32_e32 v19, v77, v76
	v_min_u32_e32 v20, v20, v21
	v_max_u32_e32 v21, v77, v76
	v_max_u32_e32 v39, v18, v19
	v_max_u32_e32 v77, v43, v42
	v_min_u32_e32 v42, v43, v42
	v_max_u32_e32 v43, v78, v79
	v_min_u32_e32 v18, v18, v19
	v_min_u32_e32 v19, v20, v21
	v_max_u32_e32 v40, v20, v21
	v_min_u32_e32 v96, v77, v95
	v_min_u32_e32 v78, v42, v43
	v_max_u32_e32 v98, v18, v19
	v_max_u32_e32 v20, v77, v95
	v_max_u32_e32 v21, v42, v43
	v_min_u32_e32 v95, v18, v19
	v_mov_b32_e32 v18, v35
; DI unsigned enc_key(float s) { const unsigned u = __float_as_uint(s); return (u & 0x80000000u) ? ~u : (u | 0x80000000u); }
; DI void merge16_desc(unsigned (&R)[16], const unsigned (&X)[16]) {
; #pragma unroll
;   for (int i = 0; i < 16; ++i) R[i] = R[i] > X[15 - i] ? R[i] : X[15 - i];
;   constexpr int JS[4] = {8, 4, 2, 1};
; #pragma unroll
;   for (int s = 0; s < 4; ++s) {
; #pragma unroll
;     for (int i = 0; i < 16; ++i) {
;       const int l = i ^ JS[s];
;       if (l > i) cswap(R[i], R[l]);
;     }
;   }
; }
; DI void phase_peer_q(const Params& p, char* smem) {
;     ...
;       for (int gi = 0; gi < 4; ++gi) {
;         unsigned X[16];
; #pragma unroll
;         for (int i = 0; i < 16; ++i) {
;           const int c = gi * 16 + i;
;           X[i] = (c < CT.n) ? ((enc_key(s1[CT.i[c]] + s2[CT.j[c]]) & ~255u) | (unsigned)(255 - (CT.i[c] * 16 + CT.j[c]))) : 0u;
;         }
;         sort16_desc(X);
;         if (gi == 0) {
; #pragma unroll
;           for (int i = 0; i < 16; ++i) B[i] = X[i];
;         } else merge16_desc(B, X);
;       }
	v_mov_b32_e32 v19, v24
	v_max_u32_e32 v76, v39, v40
	v_min_u32_e32 v79, v96, v78
	v_min_u32_e32 v42, v20, v21
	v_min_u32_e32 v39, v39, v40
	v_max_u32_e32 v40, v96, v78
	v_max_u32_e32 v96, v20, v21
	v_pk_add_f32 v[20:21], v[36:37], v[18:19] op_sel_hi:[0,1]
	v_not_b32_e32 v35, v21
	v_or_b32_e32 v102, 0x80000000, v21
	v_cmp_gt_i32_e32 vcc, 0, v21
	v_min_u32_e32 v94, v157, v81
	v_max_u32_e32 v81, v157, v81
	v_cndmask_b32_e32 v21, v102, v35, vcc
	v_not_b32_e32 v35, v20
	v_or_b32_e32 v102, 0x80000000, v20
	v_cmp_gt_i32_e32 vcc, 0, v20
	v_and_b32_e32 v21, 0xffffff00, v21
	v_or_b32_e32 v21, 0xce, v21
	v_cndmask_b32_e32 v20, v102, v35, vcc
	v_and_b32_e32 v20, 0xffffff00, v20
	v_or_b32_e32 v20, 0xcd, v20
	v_max_u32_e32 v35, v20, v21
	v_min_u32_e32 v102, v37, v38
	v_min_u32_e32 v20, v20, v21
	v_max_u32_e32 v21, v37, v38
	v_max_u32_e32 v103, v35, v102
	v_max_u32_e32 v37, v20, v21
	v_min_u32_e32 v35, v35, v102
	v_min_u32_e32 v20, v20, v21
	v_max_u32_e32 v102, v104, v105
	v_max_u32_e32 v38, v103, v37
	v_max_u32_e32 v21, v35, v20
	v_min_u32_e32 v80, v102, v44
	v_min_u32_e32 v37, v103, v37
	v_min_u32_e32 v20, v35, v20
	v_max_u32_e32 v35, v102, v44
	v_max_u32_e32 v97, v76, v79
	v_max_u32_e32 v43, v98, v42
	v_max_u32_e32 v78, v39, v40
	v_max_u32_e32 v99, v95, v96
	v_min_u32_e32 v158, v38, v94
	v_min_u32_e32 v104, v21, v80
	v_min_u32_e32 v103, v37, v81
	v_min_u32_e32 v44, v20, v35
	v_min_u32_e32 v76, v76, v79
	v_min_u32_e32 v42, v98, v42
	v_min_u32_e32 v39, v39, v40
	v_min_u32_e32 v40, v95, v96
	v_max_u32_e32 v38, v38, v94
	v_max_u32_e32 v21, v21, v80
	v_max_u32_e32 v37, v37, v81
	v_max_u32_e32 v20, v20, v35
	v_max_u32_e32 v77, v97, v43
	v_max_u32_e32 v100, v78, v99
	v_min_u32_e32 v105, v158, v104
	v_min_u32_e32 v102, v103, v44
	v_max_u32_e32 v79, v76, v42
	v_max_u32_e32 v95, v39, v40
	v_min_u32_e32 v80, v38, v21
	v_min_u32_e32 v35, v37, v20
	v_min_u32_e32 v43, v97, v43
	v_min_u32_e32 v78, v78, v99
	v_max_u32_e32 v99, v158, v104
	v_max_u32_e32 v44, v103, v44
	v_min_u32_e32 v42, v76, v42
	v_min_u32_e32 v39, v39, v40
	v_max_u32_e32 v21, v38, v21
	v_max_u32_e32 v20, v37, v20
	v_max_u32_e32 v101, v77, v100
	v_min_u32_e32 v157, v105, v102
	v_max_u32_e32 v96, v79, v95
	v_min_u32_e32 v81, v80, v35
	v_max_u32_e32 v97, v43, v78
	v_min_u32_e32 v103, v99, v44
	v_max_u32_e32 v40, v42, v39
	v_min_u32_e32 v37, v21, v20
	v_min_u32_e32 v159, v101, v157
	v_min_u32_e32 v94, v96, v81
	v_min_u32_e32 v104, v97, v103
	v_min_u32_e32 v38, v40, v37
	v_min_u32_e32 v98, v159, v94
	v_min_u32_e32 v76, v104, v38
	v_min_u32_e32 v77, v77, v100
	v_max_u32_e32 v100, v105, v102
	v_min_u32_e32 v79, v79, v95
	v_max_u32_e32 v35, v80, v35
	v_min_u32_e32 v43, v43, v78
	v_max_u32_e32 v44, v99, v44
	v_min_u32_e32 v39, v42, v39
	v_max_u32_e32 v20, v21, v20
	v_max_u32_e32 v94, v159, v94
	v_max_u32_e32 v38, v104, v38
	v_min_u32_e32 v158, v98, v76
	v_min_u32_e32 v102, v77, v100
	v_min_u32_e32 v80, v79, v35
	v_min_u32_e32 v78, v43, v44
	v_min_u32_e32 v21, v39, v20
	v_max_u32_e32 v76, v98, v76
	v_min_u32_e32 v98, v94, v38
	v_max_u32_e32 v38, v94, v38
	v_max_u32_e32 v94, v101, v157
	v_max_u32_e32 v81, v96, v81
	v_max_u32_e32 v97, v97, v103
	v_max_u32_e32 v37, v40, v37
	v_max_u32_e32 v77, v77, v100
	v_max_u32_e32 v35, v79, v35
	v_max_u32_e32 v43, v43, v44
	v_max_u32_e32 v20, v39, v20
	v_min_u32_e32 v95, v102, v80
	v_min_u32_e32 v42, v78, v21
	v_max_u32_e32 v80, v102, v80
	v_max_u32_e32 v21, v78, v21
	v_min_u32_e32 v96, v94, v81
	v_min_u32_e32 v40, v97, v37
	v_min_u32_e32 v79, v77, v35
	v_min_u32_e32 v39, v43, v20
	v_max_u32_e32 v81, v94, v81
	v_max_u32_e32 v37, v97, v37
	v_max_u32_e32 v35, v77, v35
	v_max_u32_e32 v20, v43, v20
	v_min_u32_e32 v99, v95, v42
	v_max_u32_e32 v42, v95, v42
	v_min_u32_e32 v78, v80, v21
	v_max_u32_e32 v21, v80, v21
	v_min_u32_e32 v101, v96, v40
	v_min_u32_e32 v44, v79, v39
	v_max_u32_e32 v40, v96, v40
	v_max_u32_e32 v39, v79, v39
	v_min_u32_e32 v94, v81, v37
	v_min_u32_e32 v43, v35, v20
	v_max_u32_e32 v37, v81, v37
	v_max_u32_e32 v20, v35, v20
	v_min_u32_e32 v105, v158, v99
	v_min_u32_e32 v95, v76, v42
	v_min_u32_e32 v102, v98, v78
	v_min_u32_e32 v80, v38, v21
	v_min_u32_e32 v100, v101, v44
	v_min_u32_e32 v79, v40, v39
	v_min_u32_e32 v77, v94, v43
	v_min_u32_e32 v35, v37, v20
	v_max3_u32 v61, v64, v61, v105
	v_max3_u32 v64, v68, v158, v99
	v_max3_u32 v56, v60, v56, v95
	v_max3_u32 v42, v69, v76, v42
	v_max3_u32 v55, v62, v55, v102
	v_max3_u32 v60, v70, v98, v78
	v_max3_u32 v54, v54, v58, v80
	v_max3_u32 v21, v71, v38, v21
	v_max3_u32 v38, v59, v63, v100
	v_max3_u32 v44, v72, v101, v44
	v_max3_u32 v53, v53, v57, v79
	v_max3_u32 v39, v73, v40, v39
	v_max3_u32 v40, v65, v67, v77
	v_max3_u32 v43, v74, v94, v43
	v_max3_u32 v31, v66, v31, v35
	v_max3_u32 v20, v75, v37, v20
	v_max_u32_e32 v35, v61, v38
	v_min_u32_e32 v37, v61, v38
	v_max_u32_e32 v38, v64, v44
	v_min_u32_e32 v44, v64, v44
	v_max_u32_e32 v57, v56, v53
	v_min_u32_e32 v53, v56, v53
	v_max_u32_e32 v56, v42, v39
	v_min_u32_e32 v39, v42, v39
	v_max_u32_e32 v42, v55, v40
	v_min_u32_e32 v40, v55, v40
	v_max_u32_e32 v55, v60, v43
	v_min_u32_e32 v43, v60, v43
	v_max_u32_e32 v58, v54, v31
	v_min_u32_e32 v31, v54, v31
	v_max_u32_e32 v54, v21, v20
	v_min_u32_e32 v20, v21, v20
	v_max_u32_e32 v21, v35, v42
	v_min_u32_e32 v35, v35, v42
	v_max_u32_e32 v42, v38, v55
	v_min_u32_e32 v38, v38, v55
	v_max_u32_e32 v55, v57, v58
	v_min_u32_e32 v57, v57, v58
	v_max_u32_e32 v58, v56, v54
	v_min_u32_e32 v54, v56, v54
	v_max_u32_e32 v56, v37, v40
	v_min_u32_e32 v37, v37, v40
	v_max_u32_e32 v40, v44, v43
	v_min_u32_e32 v43, v44, v43
	v_max_u32_e32 v44, v53, v31
	v_min_u32_e32 v31, v53, v31
	v_max_u32_e32 v53, v39, v20
	v_min_u32_e32 v20, v39, v20
; DI unsigned enc_key(float s) { const unsigned u = __float_as_uint(s); return (u & 0x80000000u) ? ~u : (u | 0x80000000u); }
; DI void phase_peer_q(const Params& p, char* smem) {
;     ...
;       for (int gi = 0; gi < 4; ++gi) {
;         unsigned X[16];
; #pragma unroll
;         for (int i = 0; i < 16; ++i) {
;           const int c = gi * 16 + i;
;           X[i] = (c < CT.n) ? ((enc_key(s1[CT.i[c]] + s2[CT.j[c]]) & ~255u) | (unsigned)(255 - (CT.i[c] * 16 + CT.j[c]))) : 0u;
;         }
;         sort16_desc(X);
;         if (gi == 0) {
; #pragma unroll
;           for (int i = 0; i < 16; ++i) B[i] = X[i];
;         } else merge16_desc(B, X);
;       }
	v_max_u32_e32 v39, v21, v55
	v_min_u32_e32 v55, v21, v55
	v_max_u32_e32 v59, v42, v58
	v_min_u32_e32 v42, v42, v58
	v_max_u32_e32 v58, v35, v57
	v_min_u32_e32 v35, v35, v57
	v_max_u32_e32 v57, v38, v54
	v_min_u32_e32 v38, v38, v54
	v_max_u32_e32 v54, v56, v44
	v_min_u32_e32 v44, v56, v44
	v_max_u32_e32 v56, v40, v53
	v_min_u32_e32 v40, v40, v53
	v_max_u32_e32 v53, v37, v31
	v_min_u32_e32 v37, v37, v31
	v_max_u32_e32 v60, v43, v20
	v_min_u32_e32 v43, v43, v20
	v_mov_b32_e32 v31, v36
	v_mov_b32_e32 v20, v25
	v_mov_b32_e32 v21, v34
	v_pk_add_f32 v[20:21], v[30:31], v[20:21]
	v_min_u32_e32 v61, v39, v59
	v_not_b32_e32 v31, v21
	v_or_b32_e32 v34, 0x80000000, v21
	v_cmp_gt_i32_e32 vcc, 0, v21
	v_min_u32_e32 v62, v55, v42
	v_min_u32_e32 v63, v58, v57
	v_cndmask_b32_e32 v21, v34, v31, vcc
	v_and_b32_e32 v21, 0xffffff00, v21
	v_or_b32_e32 v31, 0xcc, v21
	v_not_b32_e32 v21, v20
	v_or_b32_e32 v34, 0x80000000, v20
	v_cmp_gt_i32_e32 vcc, 0, v20
	v_pk_add_f32 v[18:19], v[30:31], v[18:19] op_sel_hi:[0,1]
	v_min_u32_e32 v64, v35, v38
	v_cndmask_b32_e32 v20, v34, v21, vcc
	v_and_b32_e32 v20, 0xffffff00, v20
	v_or_b32_e32 v34, 0xbf, v20
	v_not_b32_e32 v20, v19
	v_or_b32_e32 v21, 0x80000000, v19
	v_cmp_gt_i32_e32 vcc, 0, v19
	v_min_u32_e32 v65, v54, v56
	v_min_u32_e32 v66, v44, v40
	v_cndmask_b32_e32 v19, v21, v20, vcc
	v_and_b32_e32 v19, 0xffffff00, v19
	v_or_b32_e32 v30, 0xbe, v19
	v_not_b32_e32 v19, v18
	v_or_b32_e32 v20, 0x80000000, v18
	v_cmp_gt_i32_e32 vcc, 0, v18
	v_min_u32_e32 v67, v53, v60
	v_min_u32_e32 v68, v37, v43
	v_cndmask_b32_e32 v18, v20, v19, vcc
	v_and_b32_e32 v18, 0xffffff00, v18
	v_or_b32_e32 v36, 0xbd, v18
	v_pk_add_f32 v[18:19], v[32:33], v[24:25] op_sel_hi:[0,1]
	v_not_b32_e32 v20, v19
	v_or_b32_e32 v21, 0x80000000, v19
	v_cmp_gt_i32_e32 vcc, 0, v19
	s_nop 1
	v_cndmask_b32_e32 v19, v21, v20, vcc
	v_and_b32_e32 v19, 0xffffff00, v19
	v_or_b32_e32 v32, 0xaf, v19
	v_not_b32_e32 v19, v18
	v_or_b32_e32 v20, 0x80000000, v18
	v_cmp_gt_i32_e32 vcc, 0, v18
	s_nop 1
	v_cndmask_b32_e32 v18, v20, v19, vcc
	v_and_b32_e32 v18, 0xffffff00, v18
	v_or_b32_e32 v69, 0xae, v18
	v_pk_add_f32 v[18:19], v[26:27], v[24:25] op_sel_hi:[0,1]
	v_not_b32_e32 v20, v19
	v_or_b32_e32 v21, 0x80000000, v19
	v_cmp_gt_i32_e32 vcc, 0, v19
	s_nop 1
	v_cndmask_b32_e32 v19, v21, v20, vcc
	v_and_b32_e32 v19, 0xffffff00, v19
	v_or_b32_e32 v26, 0x9f, v19
	v_not_b32_e32 v19, v18
	v_or_b32_e32 v20, 0x80000000, v18
	v_cmp_gt_i32_e32 vcc, 0, v18
	s_nop 1
	v_cndmask_b32_e32 v18, v20, v19, vcc
	v_and_b32_e32 v18, 0xffffff00, v18
	v_or_b32_e32 v70, 0x9e, v18
	v_pk_add_f32 v[18:19], v[28:29], v[24:25] op_sel_hi:[0,1]
	v_not_b32_e32 v20, v19
	v_or_b32_e32 v21, 0x80000000, v19
	v_cmp_gt_i32_e32 vcc, 0, v19
	s_nop 1
	v_cndmask_b32_e32 v19, v21, v20, vcc
	v_not_b32_e32 v20, v18
	v_or_b32_e32 v21, 0x80000000, v18
	v_cmp_gt_i32_e32 vcc, 0, v18
	v_and_b32_e32 v19, 0xffffff00, v19
	v_or_b32_e32 v19, 0x8f, v19
	v_cndmask_b32_e32 v18, v21, v20, vcc
	v_and_b32_e32 v18, 0xffffff00, v18
	v_or_b32_e32 v24, 0x8e, v18
	v_xor_b32_e32 v18, -1, v49
	v_cmp_gt_i32_e32 vcc, 0, v15
	v_xor_b32_e32 v20, -1, v50
	v_min_u32_e32 v49, v32, v69
	v_cndmask_b32_e32 v21, v18, v52, vcc
	v_cmp_gt_i32_e32 vcc, 0, v14
	v_mov_b32_e32 v18, v25
	v_max_u32_e32 v32, v32, v69
	v_cndmask_b32_e32 v20, v20, v51, vcc
	v_pk_add_f32 v[20:21], v[18:19], v[20:21] op_sel_hi:[0,1]
	v_not_b32_e32 v25, v20
	v_or_b32_e32 v28, 0x80000000, v20
	v_cmp_gt_i32_e32 vcc, 0, v20
	s_nop 1
	v_cndmask_b32_e32 v20, v28, v25, vcc
	v_and_b32_e32 v20, 0xffffff00, v20
	v_or_b32_e32 v25, 0x7f, v20
	v_not_b32_e32 v20, v21
	v_or_b32_e32 v28, 0x80000000, v21
	v_cmp_gt_i32_e32 vcc, 0, v21
	s_nop 1
	v_cndmask_b32_e32 v20, v28, v20, vcc
	v_and_b32_e32 v20, 0xffffff00, v20
	v_or_b32_e32 v28, 0x6f, v20
	v_xor_b32_e32 v20, -1, v45
	v_cmp_gt_i32_e32 vcc, 0, v17
	v_xor_b32_e32 v45, -1, v46
	v_min_u32_e32 v72, v28, v25
	v_cndmask_b32_e32 v21, v20, v48, vcc
	v_cmp_gt_i32_e32 vcc, 0, v16
	v_max_u32_e32 v48, v70, v26
	v_min_u32_e32 v26, v70, v26
	v_cndmask_b32_e32 v20, v45, v47, vcc
	v_pk_add_f32 v[20:21], v[18:19], v[20:21] op_sel_hi:[0,1]
	v_not_b32_e32 v45, v20
	v_or_b32_e32 v46, 0x80000000, v20
	v_cmp_gt_i32_e32 vcc, 0, v20
	v_min_u32_e32 v50, v48, v49
	v_min_u32_e32 v51, v26, v32
	v_cndmask_b32_e32 v20, v46, v45, vcc
	v_and_b32_e32 v20, 0xffffff00, v20
	v_or_b32_e32 v45, 0x5f, v20
	v_not_b32_e32 v20, v21
	v_or_b32_e32 v46, 0x80000000, v21
	v_cmp_gt_i32_e32 vcc, 0, v21
	v_min_u32_e32 v21, v36, v30
	v_max_u32_e32 v30, v36, v30
	v_cndmask_b32_e32 v20, v46, v20, vcc
	v_and_b32_e32 v20, 0xffffff00, v20
	v_or_b32_e32 v46, 0x4f, v20
	v_max_u32_e32 v20, v31, v34
	v_min_u32_e32 v31, v31, v34
	v_max_u32_e32 v47, v20, v21
	v_max_u32_e32 v34, v31, v30
	v_min_u32_e32 v20, v20, v21
	v_min_u32_e32 v21, v31, v30
	v_max_u32_e32 v36, v47, v34
	v_min_u32_e32 v52, v50, v51
	v_max_u32_e32 v30, v20, v21
	v_min_u32_e32 v34, v47, v34
	v_max_u32_e32 v47, v50, v51
	v_min_u32_e32 v51, v20, v21
	v_xor_b32_e32 v20, -1, v27
	v_cmp_gt_i32_e32 vcc, 0, v11
	v_xor_b32_e32 v27, -1, v29
	v_max_u32_e32 v31, v48, v49
	v_cndmask_b32_e32 v21, v20, v41, vcc
	v_cmp_gt_i32_e32 vcc, 0, v10
	v_max_u32_e32 v26, v26, v32
	v_min_u32_e32 v32, v31, v26
	v_cndmask_b32_e32 v20, v27, v33, vcc
	v_pk_add_f32 v[20:21], v[18:19], v[20:21] op_sel_hi:[0,1]
	v_not_b32_e32 v27, v20
	v_or_b32_e32 v29, 0x80000000, v20
	v_cmp_gt_i32_e32 vcc, 0, v20
	v_max_u32_e32 v26, v31, v26
	v_max_u32_e32 v69, v36, v52
	v_cndmask_b32_e32 v20, v29, v27, vcc
	v_not_b32_e32 v27, v21
	v_or_b32_e32 v29, 0x80000000, v21
	v_cmp_gt_i32_e32 vcc, 0, v21
	v_and_or_b32 v20, v20, s66, 63
	v_max_u32_e32 v48, v30, v32
	v_cndmask_b32_e32 v21, v29, v27, vcc
; DI unsigned enc_key(float s) { const unsigned u = __float_as_uint(s); return (u & 0x80000000u) ? ~u : (u | 0x80000000u); }
; DI void merge16_desc(unsigned (&R)[16], const unsigned (&X)[16]) {
; #pragma unroll
;   for (int i = 0; i < 16; ++i) R[i] = R[i] > X[15 - i] ? R[i] : X[15 - i];
;   constexpr int JS[4] = {8, 4, 2, 1};
; #pragma unroll
;   for (int s = 0; s < 4; ++s) {
; #pragma unroll
;     for (int i = 0; i < 16; ++i) {
;       const int l = i ^ JS[s];
;       if (l > i) cswap(R[i], R[l]);
;     }
;   }
; }
; DI void phase_peer_q(const Params& p, char* smem) {
;     ...
;       for (int gi = 0; gi < 4; ++gi) {
;         unsigned X[16];
; #pragma unroll
;         for (int i = 0; i < 16; ++i) {
;           const int c = gi * 16 + i;
;           X[i] = (c < CT.n) ? ((enc_key(s1[CT.i[c]] + s2[CT.j[c]]) & ~255u) | (unsigned)(255 - (CT.i[c] * 16 + CT.j[c]))) : 0u;
;         }
;         sort16_desc(X);
;         if (gi == 0) {
; #pragma unroll
;           for (int i = 0; i < 16; ++i) B[i] = X[i];
;         } else merge16_desc(B, X);
;       }
	v_and_or_b32 v21, v21, s66, 47
	v_max_u32_e32 v27, v21, v20
	v_min_u32_e32 v29, v45, v46
	v_min_u32_e32 v20, v21, v20
	v_max_u32_e32 v21, v45, v46
	v_max_u32_e32 v46, v19, v24
	v_min_u32_e32 v19, v19, v24
	v_max_u32_e32 v24, v28, v25
	v_max_u32_e32 v33, v27, v29
	v_max_u32_e32 v41, v20, v21
	v_min_u32_e32 v73, v46, v72
	v_min_u32_e32 v25, v19, v24
	v_min_u32_e32 v27, v27, v29
	v_min_u32_e32 v20, v20, v21
	v_max_u32_e32 v29, v46, v72
	v_max_u32_e32 v19, v19, v24
	v_max_u32_e32 v45, v33, v41
	v_min_u32_e32 v28, v73, v25
	v_max_u32_e32 v21, v27, v20
	v_min_u32_e32 v24, v29, v19
	v_min_u32_e32 v33, v33, v41
	v_max_u32_e32 v25, v73, v25
	v_min_u32_e32 v20, v27, v20
	v_max_u32_e32 v19, v29, v19
	v_max_u32_e32 v50, v34, v47
	v_max_u32_e32 v31, v51, v26
	v_min_u32_e32 v74, v45, v28
	v_min_u32_e32 v46, v21, v24
	v_min_u32_e32 v41, v33, v25
	v_min_u32_e32 v27, v20, v19
	v_min_u32_e32 v36, v36, v52
	v_min_u32_e32 v30, v30, v32
	v_min_u32_e32 v34, v34, v47
	v_min_u32_e32 v26, v51, v26
	v_max_u32_e32 v28, v45, v28
	v_max_u32_e32 v21, v21, v24
	v_max_u32_e32 v25, v33, v25
	v_max_u32_e32 v19, v20, v19
	v_max_u32_e32 v49, v69, v48
	v_max_u32_e32 v70, v50, v31
	v_min_u32_e32 v72, v74, v46
	v_min_u32_e32 v29, v41, v27
	v_max_u32_e32 v32, v36, v30
	v_max_u32_e32 v47, v34, v26
	v_min_u32_e32 v24, v28, v21
	v_min_u32_e32 v20, v25, v19
	v_min_u32_e32 v48, v69, v48
	v_min_u32_e32 v31, v50, v31
	v_max_u32_e32 v46, v74, v46
	v_max_u32_e32 v27, v41, v27
	v_min_u32_e32 v30, v36, v30
	v_min_u32_e32 v26, v34, v26
	v_max_u32_e32 v21, v28, v21
	v_max_u32_e32 v19, v25, v19
	v_max_u32_e32 v71, v49, v70
	v_min_u32_e32 v73, v72, v29
	v_max_u32_e32 v51, v32, v47
	v_min_u32_e32 v33, v24, v20
	v_max_u32_e32 v50, v48, v31
	v_min_u32_e32 v41, v46, v27
	v_max_u32_e32 v34, v30, v26
	v_min_u32_e32 v25, v21, v19
	v_min_u32_e32 v75, v71, v73
	v_min_u32_e32 v45, v51, v33
	v_min_u32_e32 v69, v50, v41
	v_min_u32_e32 v28, v34, v25
	v_min_u32_e32 v52, v75, v45
	v_min_u32_e32 v36, v69, v28
	v_min_u32_e32 v49, v49, v70
	v_max_u32_e32 v29, v72, v29
	v_min_u32_e32 v32, v32, v47
	v_max_u32_e32 v20, v24, v20
	v_min_u32_e32 v31, v48, v31
	v_max_u32_e32 v27, v46, v27
	v_min_u32_e32 v26, v30, v26
	v_max_u32_e32 v19, v21, v19
	v_max_u32_e32 v45, v75, v45
	v_max_u32_e32 v28, v69, v28
	v_min_u32_e32 v74, v52, v36
	v_min_u32_e32 v70, v49, v29
	v_min_u32_e32 v24, v32, v20
	v_min_u32_e32 v46, v31, v27
	v_min_u32_e32 v21, v26, v19
	v_max_u32_e32 v36, v52, v36
	v_min_u32_e32 v52, v45, v28
	v_max_u32_e32 v28, v45, v28
	v_max_u32_e32 v45, v71, v73
	v_max_u32_e32 v33, v51, v33
	v_max_u32_e32 v41, v50, v41
	v_max_u32_e32 v25, v34, v25
	v_max_u32_e32 v29, v49, v29
	v_max_u32_e32 v20, v32, v20
	v_max_u32_e32 v27, v31, v27
	v_max_u32_e32 v19, v26, v19
	v_min_u32_e32 v47, v70, v24
	v_min_u32_e32 v30, v46, v21
	v_max_u32_e32 v24, v70, v24
	v_max_u32_e32 v21, v46, v21
	v_min_u32_e32 v51, v45, v33
	v_min_u32_e32 v34, v41, v25
	v_min_u32_e32 v32, v29, v20
	v_min_u32_e32 v26, v27, v19
	v_max_u32_e32 v33, v45, v33
	v_max_u32_e32 v25, v41, v25
	v_max_u32_e32 v20, v29, v20
	v_max_u32_e32 v19, v27, v19
	v_min_u32_e32 v48, v47, v30
	v_max_u32_e32 v30, v47, v30
	v_min_u32_e32 v46, v24, v21
	v_max_u32_e32 v21, v24, v21
	v_min_u32_e32 v50, v51, v34
	v_min_u32_e32 v31, v32, v26
	v_max_u32_e32 v34, v51, v34
	v_max_u32_e32 v26, v32, v26
	v_min_u32_e32 v41, v33, v25
	v_min_u32_e32 v27, v20, v19
	v_max_u32_e32 v25, v33, v25
	v_max_u32_e32 v19, v20, v19
	v_min_u32_e32 v72, v74, v48
	v_min_u32_e32 v47, v36, v30
	v_min_u32_e32 v69, v52, v46
	v_min_u32_e32 v24, v28, v21
	v_min_u32_e32 v49, v50, v31
	v_min_u32_e32 v32, v34, v26
	v_min_u32_e32 v29, v41, v27
	v_min_u32_e32 v20, v25, v19
	v_max3_u32 v33, v39, v59, v72
	v_max3_u32 v39, v61, v74, v48
	v_max3_u32 v42, v55, v42, v47
	v_max3_u32 v30, v62, v36, v30
	v_max3_u32 v36, v58, v57, v69
	v_max3_u32 v45, v63, v52, v46
	v_max3_u32 v24, v35, v38, v24
	v_max3_u32 v21, v64, v28, v21
	v_max3_u32 v28, v54, v56, v49
	v_max3_u32 v31, v65, v50, v31
	v_max3_u32 v32, v44, v40, v32
	v_max3_u32 v26, v66, v34, v26
	v_max3_u32 v29, v53, v60, v29
	v_max3_u32 v27, v67, v41, v27
	v_max3_u32 v20, v37, v43, v20
	v_max3_u32 v19, v68, v25, v19
	v_max_u32_e32 v25, v33, v28
	v_min_u32_e32 v28, v33, v28
	v_max_u32_e32 v33, v39, v31
	v_min_u32_e32 v31, v39, v31
	v_max_u32_e32 v34, v42, v32
	v_min_u32_e32 v32, v42, v32
	v_max_u32_e32 v35, v30, v26
	v_min_u32_e32 v26, v30, v26
	v_max_u32_e32 v30, v36, v29
	v_min_u32_e32 v29, v36, v29
	v_max_u32_e32 v36, v45, v27
	v_min_u32_e32 v27, v45, v27
	v_max_u32_e32 v37, v24, v20
	v_min_u32_e32 v20, v24, v20
	v_max_u32_e32 v24, v21, v19
	v_min_u32_e32 v19, v21, v19
	v_max_u32_e32 v21, v25, v30
	v_min_u32_e32 v25, v25, v30
	v_max_u32_e32 v30, v33, v36
	v_min_u32_e32 v33, v33, v36
	v_max_u32_e32 v36, v34, v37
	v_min_u32_e32 v34, v34, v37
	v_max_u32_e32 v37, v35, v24
	v_min_u32_e32 v24, v35, v24
	v_max_u32_e32 v35, v28, v29
	v_min_u32_e32 v28, v28, v29
	v_max_u32_e32 v29, v31, v27
	v_min_u32_e32 v27, v31, v27
	v_max_u32_e32 v31, v32, v20
	v_min_u32_e32 v20, v32, v20
	v_max_u32_e32 v32, v26, v19
	v_min_u32_e32 v19, v26, v19
	v_max_u32_e32 v26, v21, v36
	v_min_u32_e32 v21, v21, v36
	v_max_u32_e32 v36, v30, v37
	v_min_u32_e32 v30, v30, v37
	v_max_u32_e32 v37, v25, v34
	v_min_u32_e32 v25, v25, v34
	v_max_u32_e32 v34, v33, v24
	v_min_u32_e32 v24, v33, v24
	v_max_u32_e32 v33, v35, v31
	v_min_u32_e32 v31, v35, v31
	v_max_u32_e32 v35, v29, v32
	v_min_u32_e32 v29, v29, v32
	v_max_u32_e32 v32, v28, v20
	v_min_u32_e32 v20, v28, v20
	v_max_u32_e32 v28, v27, v19
	v_min_u32_e32 v27, v27, v19
	v_pk_add_f32 v[18:19], v[22:23], v[18:19] op_sel_hi:[1,0]
	v_max_u32_e32 v38, v26, v36
; DI float dec_key(unsigned k) { const unsigned u = (k & 0x80000000u) ? (k & 0x7fffffffu) : ~k; return __uint_as_float(u); }
; DI void phase_peer_q(const Params& p, char* smem) {
;     ...
;         if (gi == 0) {
; #pragma unroll
;           for (int i = 0; i < 16; ++i) B[i] = X[i];
;         } else merge16_desc(B, X);
;       }
;       float e[16], sum = 0.f;
;       const float s0 = dec_key(B[0] & ~255u);
; #pragma unroll
;       for (int i = 0; i < 16; ++i) { e[i] = __expf(dec_key(B[i] & ~255u) - s0); sum += e[i]; }
	v_not_b32_e32 v22, v19
	v_or_b32_e32 v23, 0x80000000, v19
	v_cmp_gt_i32_e32 vcc, 0, v19
	v_min_u32_e32 v26, v26, v36
	v_max_u32_e32 v36, v21, v30
	v_cndmask_b32_e32 v19, v23, v22, vcc
	v_not_b32_e32 v22, v18
	v_or_b32_e32 v23, 0x80000000, v18
	v_cmp_gt_i32_e32 vcc, 0, v18
	v_and_or_b32 v19, v19, s66, 31
	v_min_u32_e32 v21, v21, v30
	v_cndmask_b32_e32 v18, v23, v22, vcc
	v_and_or_b32 v18, v18, s66, 15
	v_max_u32_e32 v30, v37, v34
	v_min_u32_e32 v34, v37, v34
	v_max_u32_e32 v37, v25, v24
	v_min_u32_e32 v24, v25, v24
	v_max_u32_e32 v25, v33, v35
	v_min_u32_e32 v33, v33, v35
	v_max_u32_e32 v35, v31, v29
	v_min_u32_e32 v29, v31, v29
	v_max_u32_e32 v31, v32, v28
	v_min_u32_e32 v28, v32, v28
	v_min_u32_e32 v32, v20, v27
	v_min_u32_e32 v41, v19, v18
	v_max3_u32 v20, v20, v27, v41
	v_max3_u32 v18, v32, v19, v18
	v_min_u32_e32 v22, v38, v25
	v_min_u32_e32 v23, v30, v31
	v_min_u32_e32 v40, v36, v35
	v_min_u32_e32 v27, v37, v20
	v_min_u32_e32 v43, v26, v33
	v_min_u32_e32 v44, v34, v28
	v_min_u32_e32 v46, v21, v29
	v_min_u32_e32 v19, v24, v18
	v_min_u32_e32 v39, v22, v23
	v_min_u32_e32 v41, v40, v27
	v_min_u32_e32 v45, v43, v44
	v_min_u32_e32 v32, v46, v19
	v_min_u32_e32 v42, v39, v41
	v_min_u32_e32 v47, v45, v32
	v_max_u32_e32 v39, v39, v41
	v_max_u32_e32 v32, v45, v32
	v_min_u32_e32 v41, v39, v32
	v_max_u32_e32 v39, v39, v32
	v_max_u32_e32 v22, v22, v23
	v_max_u32_e32 v23, v40, v27
	v_max_u32_e32 v32, v43, v44
	v_max_u32_e32 v19, v46, v19
	v_min_u32_e32 v27, v22, v23
	v_min_u32_e32 v40, v32, v19
	v_max_u32_e32 v22, v22, v23
	v_max_u32_e32 v19, v32, v19
	v_min_u32_e32 v51, v22, v19
	v_max_u32_e32 v53, v22, v19
	v_max_u32_e32 v19, v38, v25
	v_max_u32_e32 v22, v30, v31
	v_max_u32_e32 v25, v36, v35
	v_max_u32_e32 v20, v37, v20
	v_max_u32_e32 v26, v26, v33
	v_max_u32_e32 v28, v34, v28
	v_max_u32_e32 v21, v21, v29
	v_max_u32_e32 v18, v24, v18
	v_min_u32_e32 v43, v27, v40
	v_max_u32_e32 v40, v27, v40
	v_min_u32_e32 v23, v19, v22
	v_min_u32_e32 v27, v25, v20
	v_min_u32_e32 v31, v26, v28
	v_min_u32_e32 v24, v21, v18
	v_min_u32_e32 v30, v23, v27
	v_min_u32_e32 v29, v31, v24
	v_max_u32_e32 v23, v23, v27
	v_max_u32_e32 v24, v31, v24
	v_min_u32_e32 v55, v23, v24
	v_max_u32_e32 v57, v23, v24
	v_max_u32_e32 v19, v19, v22
	v_max_u32_e32 v20, v25, v20
	v_max_u32_e32 v23, v26, v28
	v_max_u32_e32 v18, v21, v18
	v_min_u32_e32 v22, v19, v20
	v_min_u32_e32 v21, v23, v18
	v_max_u32_e32 v19, v19, v20
	v_max_u32_e32 v18, v23, v18
	v_min_u32_e32 v62, v19, v18
	v_max_u32_e32 v61, v22, v21
	v_max_u32_e32 v63, v19, v18
	v_and_b32_e32 v18, 0x7fffff00, v62
	v_bitop3_b32 v19, v62, s76, v62 bitop3:0xcf
	v_cmp_gt_i32_e32 vcc, 0, v62
	v_min_u32_e32 v59, v22, v21
	v_bitop3_b32 v20, v61, s76, v61 bitop3:0xcf
	v_cndmask_b32_e32 v18, v19, v18, vcc
	v_and_b32_e32 v19, 0x7fffff00, v61
	v_cmp_gt_i32_e32 vcc, 0, v61
	v_bitop3_b32 v21, v59, s76, v59 bitop3:0xcf
	v_bitop3_b32 v22, v57, s76, v57 bitop3:0xcf
	v_cndmask_b32_e32 v19, v20, v19, vcc
	v_and_b32_e32 v20, 0x7fffff00, v59
	v_cmp_gt_i32_e32 vcc, 0, v59
	v_min_u32_e32 v36, v30, v29
	v_max_u32_e32 v29, v30, v29
	v_cndmask_b32_e32 v20, v21, v20, vcc
	v_and_b32_e32 v21, 0x7fffff00, v57
	v_cmp_gt_i32_e32 vcc, 0, v57
	v_bitop3_b32 v23, v55, s76, v55 bitop3:0xcf
	v_bitop3_b32 v24, v29, s76, v29 bitop3:0xcf
	v_cndmask_b32_e32 v21, v22, v21, vcc
	v_and_b32_e32 v22, 0x7fffff00, v55
	v_cmp_gt_i32_e32 vcc, 0, v55
	v_bitop3_b32 v25, v36, s76, v36 bitop3:0xcf
	v_bitop3_b32 v26, v53, s76, v53 bitop3:0xcf
	v_cndmask_b32_e32 v22, v23, v22, vcc
	v_and_b32_e32 v23, 0x7fffff00, v29
	v_cmp_gt_i32_e32 vcc, 0, v29
	v_bitop3_b32 v27, v51, s76, v51 bitop3:0xcf
	v_min_u32_e32 v48, v42, v47
	v_cndmask_b32_e32 v23, v24, v23, vcc
	v_and_b32_e32 v24, 0x7fffff00, v36
	v_cmp_gt_i32_e32 vcc, 0, v36
	v_max_u32_e32 v42, v42, v47
	v_and_b32_e32 v31, 0x7fffff00, v48
	v_cndmask_b32_e32 v24, v25, v24, vcc
	v_and_b32_e32 v25, 0x7fffff00, v53
	v_cmp_gt_i32_e32 vcc, 0, v53
	v_and_b32_e32 v30, 0x7fffff00, v63
	v_not_b32_e32 v37, v36
	v_cndmask_b32_e32 v25, v26, v25, vcc
	v_and_b32_e32 v26, 0x7fffff00, v51
	v_cmp_gt_i32_e32 vcc, 0, v51
	v_not_b32_e32 v38, v29
	v_not_b32_e32 v56, v55
	v_cndmask_b32_e32 v28, v27, v26, vcc
	v_and_b32_e32 v26, 0x7fffff00, v40
	v_bitop3_b32 v27, v40, s76, v40 bitop3:0xcf
	v_cmp_gt_i32_e32 vcc, 0, v40
	v_not_b32_e32 v58, v57
	v_not_b32_e32 v60, v59
	v_cndmask_b32_e32 v64, v27, v26, vcc
	v_and_b32_e32 v26, 0x7fffff00, v43
	v_bitop3_b32 v27, v43, s76, v43 bitop3:0xcf
	v_cmp_gt_i32_e32 vcc, 0, v43
	v_lshrrev_b32_e32 v60, 2, v60
	v_lshrrev_b32_e32 v58, 2, v58
	v_cndmask_b32_e32 v65, v27, v26, vcc
	v_and_b32_e32 v26, 0x7fffff00, v39
	v_bitop3_b32 v27, v39, s76, v39 bitop3:0xcf
	v_cmp_gt_i32_e32 vcc, 0, v39
	v_lshrrev_b32_e32 v56, 2, v56
	v_lshrrev_b32_e32 v38, 2, v38
	v_cndmask_b32_e32 v66, v27, v26, vcc
	v_and_b32_e32 v26, 0x7fffff00, v41
	v_bitop3_b32 v27, v41, s76, v41 bitop3:0xcf
	v_cmp_gt_i32_e32 vcc, 0, v41
	v_lshrrev_b32_e32 v37, 2, v37
	v_and_b32_e32 v60, 60, v60
	v_cndmask_b32_e32 v67, v27, v26, vcc
	v_and_b32_e32 v26, 0x7fffff00, v42
	v_bitop3_b32 v27, v42, s76, v42 bitop3:0xcf
	v_cmp_gt_i32_e32 vcc, 0, v42
	v_bitop3_b32 v59, v59, 15, v59 bitop3:0xc
	v_and_b32_e32 v58, 60, v58
	v_cndmask_b32_e32 v68, v27, v26, vcc
	v_and_b32_e32 v27, 0xffffff00, v48
	v_and_b32_e32 v26, 0xffffff00, v63
	v_xor_b32_e32 v27, -1, v27
	v_cmp_gt_i32_e32 vcc, 0, v48
	v_xor_b32_e32 v26, -1, v26
	v_bitop3_b32 v57, v57, 15, v57 bitop3:0xc
	v_cndmask_b32_e32 v69, v27, v31, vcc
	v_cmp_gt_i32_e32 vcc, 0, v63
	v_and_b32_e32 v56, 60, v56
	v_bitop3_b32 v55, v55, 15, v55 bitop3:0xc
	v_cndmask_b32_e32 v70, v26, v30, vcc
	v_sub_f32_e32 v18, v18, v70
	v_mul_f32_e32 v18, 0x3fb8aa3b, v18
; DI float dec_key(unsigned k) { const unsigned u = (k & 0x80000000u) ? (k & 0x7fffffffu) : ~k; return __uint_as_float(u); }
; DI void phase_peer_q(const Params& p, char* smem) {
;     ...
;       float e[16], sum = 0.f;
;       const float s0 = dec_key(B[0] & ~255u);
; #pragma unroll
;       for (int i = 0; i < 16; ++i) { e[i] = __expf(dec_key(B[i] & ~255u) - s0); sum += e[i]; }
;       const float inv = 1.f / sum;
;       int ids[16];
; #pragma unroll
;       for (int i = 0; i < 16; ++i) {
;         const int flat = 255 - (int)(B[i] & 255u);
;         const int i1 = 127 - (int)(xch[(tok * 2 + 0) * 16 + (flat >> 4)] & 127u);
;         const int i2 = 127 - (int)(xch[(tok * 2 + 1) * 16 + (flat & 15)] & 127u);
;         ids[i] = i1 * 128 + i2;
;         e[i] *= inv;
;       }
	v_sub_f32_e32 v26, v70, v70
	v_exp_f32_e32 v33, v18
	v_sub_f32_e32 v18, v19, v70
	v_sub_f32_e32 v19, v21, v70
	v_mul_f32_e32 v26, 0x3fb8aa3b, v26
	v_mul_f32_e32 v19, 0x3fb8aa3b, v19
	v_exp_f32_e32 v32, v26
	v_exp_f32_e32 v26, v19
	v_sub_f32_e32 v19, v22, v70
	v_mul_f32_e32 v19, 0x3fb8aa3b, v19
	v_exp_f32_e32 v27, v19
	v_sub_f32_e32 v19, v23, v70
	v_mul_f32_e32 v18, 0x3fb8aa3b, v18
	v_mul_f32_e32 v19, 0x3fb8aa3b, v19
	v_exp_f32_e32 v34, v18
	v_sub_f32_e32 v18, v20, v70
	v_exp_f32_e32 v30, v19
	v_sub_f32_e32 v19, v24, v70
	v_mul_f32_e32 v18, 0x3fb8aa3b, v18
	v_mul_f32_e32 v19, 0x3fb8aa3b, v19
	v_exp_f32_e32 v35, v18
	v_exp_f32_e32 v31, v19
	v_sub_f32_e32 v19, v25, v70
	v_add_f32_e32 v18, 0, v32
	v_mul_f32_e32 v19, 0x3fb8aa3b, v19
	v_add_f32_e32 v18, v33, v18
	v_exp_f32_e32 v22, v19
	v_sub_f32_e32 v19, v28, v70
	v_add_f32_e32 v18, v34, v18
	v_mul_f32_e32 v19, 0x3fb8aa3b, v19
	v_add_f32_e32 v18, v35, v18
	v_exp_f32_e32 v23, v19
	v_sub_f32_e32 v19, v64, v70
	v_add_f32_e32 v18, v26, v18
	v_mul_f32_e32 v19, 0x3fb8aa3b, v19
	v_add_f32_e32 v18, v27, v18
	v_exp_f32_e32 v24, v19
	v_sub_f32_e32 v19, v65, v70
	v_add_f32_e32 v18, v30, v18
	v_mul_f32_e32 v19, 0x3fb8aa3b, v19
	v_add_f32_e32 v18, v31, v18
	v_exp_f32_e32 v25, v19
	v_add_f32_e32 v18, v22, v18
	v_add_f32_e32 v18, v23, v18
	v_add_f32_e32 v18, v24, v18
	v_add_f32_e32 v28, v25, v18
	v_sub_f32_e32 v18, v66, v70
	v_mul_f32_e32 v18, 0x3fb8aa3b, v18
	v_sub_f32_e32 v19, v67, v70
	v_exp_f32_e32 v18, v18
	v_mul_f32_e32 v19, 0x3fb8aa3b, v19
	v_sub_f32_e32 v20, v68, v70
	v_exp_f32_e32 v19, v19
	v_mul_f32_e32 v20, 0x3fb8aa3b, v20
	v_sub_f32_e32 v21, v69, v70
	v_exp_f32_e32 v20, v20
	v_mul_f32_e32 v21, 0x3fb8aa3b, v21
	v_exp_f32_e32 v21, v21
	v_add_f32_e32 v28, v18, v28
	v_add_f32_e32 v28, v19, v28
	v_add_f32_e32 v28, v20, v28
	v_add_f32_e32 v28, v21, v28
	v_div_scale_f32 v64, s[0:1], v28, v28, 1.0
	v_rcp_f32_e32 v65, v64
	v_not_b32_e32 v66, v61
	v_not_b32_e32 v67, v62
	v_not_b32_e32 v68, v63
	v_fma_f32 v69, -v64, v65, 1.0
	v_fmac_f32_e32 v65, v69, v65
	v_div_scale_f32 v69, vcc, 1.0, v28, 1.0
	v_mul_f32_e32 v70, v69, v65
	v_fma_f32 v71, -v64, v70, v69
	v_fmac_f32_e32 v70, v71, v65
	v_fma_f32 v64, -v64, v70, v69
	v_div_fmas_f32 v64, v64, v65, v70
	v_div_fixup_f32 v28, v64, v28, 1.0
	v_lshrrev_b32_e32 v64, 2, v68
	v_lshrrev_b32_e32 v65, 2, v67
	v_lshrrev_b32_e32 v66, 2, v66
	v_and_b32_e32 v64, 60, v64
	v_bitop3_b32 v63, v63, 15, v63 bitop3:0xc
	v_and_b32_e32 v65, 60, v65
	v_bitop3_b32 v62, v62, 15, v62 bitop3:0xc
	v_and_b32_e32 v66, 60, v66
	v_bitop3_b32 v61, v61, 15, v61 bitop3:0xc
	v_and_b32_e32 v38, 60, v38
	v_bitop3_b32 v29, v29, 15, v29 bitop3:0xc
	v_and_b32_e32 v37, 60, v37
	v_add_u32_e32 v64, v124, v64
	v_lshl_add_u32 v63, v63, 2, v124
	v_add_u32_e32 v65, v124, v65
	v_lshl_add_u32 v62, v62, 2, v124
	v_add_u32_e32 v66, v124, v66
	v_lshl_add_u32 v61, v61, 2, v124
	v_add_u32_e32 v60, v124, v60
	v_lshl_add_u32 v59, v59, 2, v124
	v_add_u32_e32 v58, v124, v58
	v_lshl_add_u32 v57, v57, 2, v124
	v_add_u32_e32 v56, v124, v56
	v_lshl_add_u32 v55, v55, 2, v124
	v_add_u32_e32 v38, v124, v38
	v_lshl_add_u32 v29, v29, 2, v124
	v_add_u32_e32 v37, v124, v37
	v_bitop3_b32 v36, v36, 15, v36 bitop3:0xc
	ds_read_b32 v64, v64
	ds_read_b32 v63, v63 offset:64
	ds_read_b32 v65, v65
	ds_read_b32 v62, v62 offset:64
	ds_read_b32 v66, v66
	ds_read_b32 v61, v61 offset:64
	ds_read_b32 v60, v60
	ds_read_b32 v59, v59 offset:64
	v_lshl_add_u32 v36, v36, 2, v124
	ds_read_b32 v58, v58
	ds_read_b32 v57, v57 offset:64
	ds_read_b32 v56, v56
	ds_read_b32 v55, v55 offset:64
	ds_read_b32 v38, v38
	ds_read_b32 v29, v29 offset:64
	ds_read_b32 v37, v37
	ds_read_b32 v67, v36 offset:64
	v_not_b32_e32 v44, v43
	v_not_b32_e32 v46, v40
	v_not_b32_e32 v52, v51
	v_not_b32_e32 v54, v53
	s_waitcnt lgkmcnt(3)
	v_lshlrev_b32_e32 v68, 7, v38
	v_lshrrev_b32_e32 v36, 2, v54
	v_lshrrev_b32_e32 v38, 2, v52
	v_lshrrev_b32_e32 v46, 2, v46
	v_lshrrev_b32_e32 v44, 2, v44
	s_waitcnt lgkmcnt(1)
	v_lshlrev_b32_e32 v69, 7, v37
	v_and_b32_e32 v36, 60, v36
	v_bitop3_b32 v37, v53, 15, v53 bitop3:0xc
	v_and_b32_e32 v38, 60, v38
	v_bitop3_b32 v51, v51, 15, v51 bitop3:0xc
	v_and_b32_e32 v46, 60, v46
	v_bitop3_b32 v40, v40, 15, v40 bitop3:0xc
	v_and_b32_e32 v44, 60, v44
	v_add_u32_e32 v36, v124, v36
	v_lshl_add_u32 v37, v37, 2, v124
	v_add_u32_e32 v38, v124, v38
	v_lshl_add_u32 v51, v51, 2, v124
	v_add_u32_e32 v46, v124, v46
	v_lshl_add_u32 v40, v40, 2, v124
	v_add_u32_e32 v44, v124, v44
	v_bitop3_b32 v43, v43, 15, v43 bitop3:0xc
	v_lshl_add_u32 v43, v43, 2, v124
	ds_read_b32 v36, v36
	ds_read_b32 v52, v37 offset:64
	ds_read_b32 v37, v38
	ds_read_b32 v51, v51 offset:64
	ds_read_b32 v38, v46
	ds_read_b32 v46, v40 offset:64
	ds_read_b32 v40, v44
	ds_read_b32 v44, v43 offset:64
	v_not_b32_e32 v45, v41
	v_not_b32_e32 v50, v39
	v_not_b32_e32 v49, v48
	v_not_b32_e32 v47, v42
	s_waitcnt lgkmcnt(7)
; DI void phase_peer_q(const Params& p, char* smem) {
;     ...
;       int ids[16];
; #pragma unroll
;       for (int i = 0; i < 16; ++i) {
;         const int flat = 255 - (int)(B[i] & 255u);
;         const int i1 = 127 - (int)(xch[(tok * 2 + 0) * 16 + (flat >> 4)] & 127u);
;         const int i2 = 127 - (int)(xch[(tok * 2 + 1) * 16 + (flat & 15)] & 127u);
;         ids[i] = i1 * 128 + i2;
;         e[i] *= inv;
;       }
;       int* di = sel_i + (size_t)(m0 + tok) * 128 + hd * 16;
;       float* dg = sel_g + (size_t)(m0 + tok) * 128 + hd * 16;
; #pragma unroll
;       for (int k = 0; k < 4; ++k) {
;         *(int4*)(di + 4 * k) = int4{ids[4 * k], ids[4 * k + 1], ids[4 * k + 2], ids[4 * k + 3]};
;         *(float4*)(dg + 4 * k) = float4{e[4 * k], e[4 * k + 1], e[4 * k + 2], e[4 * k + 3]};
;       }
	v_lshlrev_b32_e32 v53, 7, v36
	s_waitcnt lgkmcnt(3)
	v_lshlrev_b32_e32 v70, 7, v38
	v_lshrrev_b32_e32 v36, 2, v50
	v_lshrrev_b32_e32 v38, 2, v45
	v_lshlrev_b32_e32 v54, 7, v37
	s_waitcnt lgkmcnt(1)
	v_lshlrev_b32_e32 v71, 7, v40
	v_and_b32_e32 v36, 60, v36
	v_bitop3_b32 v37, v39, 15, v39 bitop3:0xc
	v_and_b32_e32 v38, 60, v38
	v_bitop3_b32 v39, v41, 15, v41 bitop3:0xc
	v_lshrrev_b32_e32 v40, 2, v47
	v_bitop3_b32 v41, v42, 15, v42 bitop3:0xc
	v_lshrrev_b32_e32 v42, 2, v49
	v_add_u32_e32 v36, v124, v36
	v_lshl_add_u32 v37, v37, 2, v124
	v_add_u32_e32 v38, v124, v38
	v_lshl_add_u32 v39, v39, 2, v124
	v_and_b32_e32 v40, 60, v40
	v_and_b32_e32 v42, 60, v42
	v_bitop3_b32 v43, v48, 15, v48 bitop3:0xc
	v_add_u32_e32 v40, v124, v40
	v_lshl_add_u32 v41, v41, 2, v124
	v_add_u32_e32 v42, v124, v42
	v_lshl_add_u32 v43, v43, 2, v124
	ds_read_b32 v36, v36
	ds_read_b32 v45, v37 offset:64
	ds_read_b32 v37, v38
	ds_read_b32 v47, v39 offset:64
	ds_read_b32 v38, v40
	ds_read_b32 v48, v41 offset:64
	ds_read_b32 v39, v42
	ds_read_b32 v49, v43 offset:64
	s_waitcnt lgkmcnt(7)
	v_lshlrev_b32_e32 v50, 7, v36
	v_or_b32_e32 v36, s80, v0
	s_waitcnt lgkmcnt(5)
	v_lshlrev_b32_e32 v72, 7, v37
	v_ashrrev_i32_e32 v37, 31, v36
	s_lshl_b32 s0, s79, 4
	v_lshlrev_b64 v[36:37], 9, v[36:37]
	s_ashr_i32 s1, s0, 31
	v_lshlrev_b32_e32 v64, 7, v64
	v_lshlrev_b32_e32 v65, 7, v65
	s_waitcnt lgkmcnt(3)
	v_lshlrev_b32_e32 v73, 7, v38
	s_waitcnt lgkmcnt(1)
	v_lshlrev_b32_e32 v74, 7, v39
	v_lshl_add_u64 v[38:39], s[46:47], 0, v[36:37]
	s_lshl_b64 s[0:1], s[0:1], 2
	v_lshl_add_u64 v[36:37], s[48:49], 0, v[36:37]
	v_lshl_add_u64 v[40:41], v[38:39], 0, s[0:1]
	v_lshl_add_u64 v[42:43], v[36:37], 0, s[0:1]
	v_and_b32_e32 v36, 0x7f, v62
	v_and_b32_e32 v37, 0x3f80, v64
	v_and_b32_e32 v38, 0x3f80, v65
	v_and_b32_e32 v39, 0x7f, v63
	v_lshlrev_b32_e32 v66, 7, v66
	v_lshlrev_b32_e32 v60, 7, v60
	v_or_b32_e32 v36, v36, v38
	v_or_b32_e32 v38, v37, v39
	v_lshlrev_b32_e32 v58, 7, v58
	v_lshlrev_b32_e32 v56, 7, v56
	v_xor_b32_e32 v37, 0x3fff, v36
	v_xor_b32_e32 v36, 0x3fff, v38
	v_and_b32_e32 v38, 0x7f, v59
	v_and_b32_e32 v39, 0x3f80, v66
	v_and_b32_e32 v59, 0x3f80, v60
	v_and_b32_e32 v60, 0x7f, v61
	v_pk_mul_f32 v[32:33], v[32:33], v[28:29] op_sel_hi:[1,0]
	v_pk_mul_f32 v[34:35], v[34:35], v[28:29] op_sel_hi:[1,0]
	v_or_b32_e32 v38, v38, v59
	v_or_b32_e32 v59, v39, v60
	global_store_dwordx4 v[42:43], v[32:35], off
	v_xor_b32_e32 v39, 0x3fff, v38
	v_xor_b32_e32 v38, 0x3fff, v59
	v_and_b32_e32 v32, 0x7f, v55
	v_and_b32_e32 v33, 0x3f80, v58
	v_and_b32_e32 v34, 0x3f80, v56
	v_and_b32_e32 v35, 0x7f, v57
	v_or_b32_e32 v32, v32, v34
	v_or_b32_e32 v34, v33, v35
	global_store_dwordx4 v[40:41], v[36:39], off
	v_xor_b32_e32 v33, 0x3fff, v32
	v_xor_b32_e32 v32, 0x3fff, v34
	v_and_b32_e32 v34, 0x7f, v67
	v_and_b32_e32 v35, 0x3f80, v68
	v_and_b32_e32 v36, 0x3f80, v69
	v_and_b32_e32 v29, 0x7f, v29
	v_or_b32_e32 v34, v34, v36
	v_or_b32_e32 v29, v35, v29
	v_xor_b32_e32 v35, 0x3fff, v34
	v_xor_b32_e32 v34, 0x3fff, v29
	global_store_dwordx4 v[40:41], v[32:35], off offset:16
	s_nop 1
	v_pk_mul_f32 v[32:33], v[26:27], v[28:29] op_sel_hi:[1,0]
	v_pk_mul_f32 v[34:35], v[30:31], v[28:29] op_sel_hi:[1,0]
	v_and_b32_e32 v26, 0x7f, v51
	v_and_b32_e32 v29, 0x3f80, v54
	v_and_b32_e32 v27, 0x3f80, v53
	v_and_b32_e32 v30, 0x7f, v52
	v_or_b32_e32 v26, v26, v29
	v_and_b32_e32 v29, 0x3f80, v71
	v_or_b32_e32 v27, v27, v30
	v_pk_mul_f32 v[22:23], v[22:23], v[28:29] op_sel_hi:[1,0]
	v_pk_mul_f32 v[24:25], v[24:25], v[28:29] op_sel_hi:[1,0]
	global_store_dwordx4 v[42:43], v[32:35], off offset:16
	v_xor_b32_e32 v31, 0x3fff, v26
	v_xor_b32_e32 v30, 0x3fff, v27
	v_and_b32_e32 v26, 0x7f, v44
	v_and_b32_e32 v27, 0x3f80, v70
	v_and_b32_e32 v32, 0x7f, v46
	global_store_dwordx4 v[42:43], v[22:25], off offset:32
	v_or_b32_e32 v26, v26, v29
	v_or_b32_e32 v27, v27, v32
	v_and_b32_e32 v22, 0x7f, v47
	v_and_b32_e32 v23, 0x3f80, v50
	v_and_b32_e32 v24, 0x3f80, v72
	v_and_b32_e32 v25, 0x7f, v45
	v_or_b32_e32 v22, v22, v24
	v_or_b32_e32 v24, v23, v25
	v_xor_b32_e32 v33, 0x3fff, v26
	v_xor_b32_e32 v32, 0x3fff, v27
	v_xor_b32_e32 v23, 0x3fff, v22
	v_xor_b32_e32 v22, 0x3fff, v24
	s_waitcnt lgkmcnt(0)
	v_and_b32_e32 v24, 0x7f, v49
	v_and_b32_e32 v25, 0x3f80, v73
	v_and_b32_e32 v26, 0x3f80, v74
	v_and_b32_e32 v27, 0x7f, v48
	v_or_b32_e32 v24, v24, v26
	v_or_b32_e32 v26, v25, v27
	v_xor_b32_e32 v25, 0x3fff, v24
	v_xor_b32_e32 v24, 0x3fff, v26
	v_pk_mul_f32 v[18:19], v[18:19], v[28:29] op_sel_hi:[1,0]
	v_pk_mul_f32 v[20:21], v[20:21], v[28:29] op_sel_hi:[1,0]
	global_store_dwordx4 v[40:41], v[30:33], off offset:32
	global_store_dwordx4 v[40:41], v[22:25], off offset:48
	global_store_dwordx4 v[42:43], v[18:21], off offset:48
	s_branch .LBB0_396
